# A2 + indexer relu fold + attention K rows gathered 128B per 8 lanes (half the line requests)
# speedup vs baseline: 1.0044x; 1.0044x over previous
; #define LAS __attribute__((address_space(3)))
; __device__ __forceinline__ void attend_one(unsigned char* ws, LAS unsigned char* lds, int wave, int bb, int t, int kvh, int lane) {
;     ...
;     bf16_t* qrow = (bf16_t*)(ws + WS_DQ) + (size_t)(bb * 8192 + t) * 2048 + kvh * 512;
;     const unsigned short* ix = (const unsigned short*)(ws + WS_IDX) + (size_t)(bb * 8192 + t) * 256;
;     const int cnt = t < 255 ? t + 1 : 256;
;     LAS unsigned* li = (LAS unsigned*)(lds + wave * 1024);
;     { const u32x2 iw = *(const u32x2*)(ix + lane * 4); *(LAS u32x4*)(li + lane * 4) = (u32x4){(iw.x & 0xffffu) << 8, (iw.x >> 16) << 8, (iw.y & 0xffffu) << 8, (iw.y >> 16) << 8}; }
;     bf16x8 qf[4];
; #pragma unroll
;     for (int kk = 0; kk < 4; ++kk) { qf[kk] = (bf16x8){0, 0, 0, 0, 0, 0, 0, 0}; if (n < 4) qf[kk] = *(const bf16x8*)(qrow + n * 128 + kk * 32 + g * 8); }
;     asm volatile("s_waitcnt vmcnt(0) lgkmcnt(0)" ::: "memory");
.LBB0_2937:
	s_ashr_i32 s6, s0, 2
	s_and_b64 s[4:5], s[10:11], exec
	s_cselect_b32 s5, s1, s0
	s_cselect_b32 s4, s25, s6
	s_and_b32 s8, s5, 3
	s_ashr_i32 s5, s4, 31
	s_lshl_b64 s[6:7], s[4:5], 12
	s_add_u32 s6, s18, s6
	s_addc_u32 s7, s19, s7
	s_lshl_b32 s9, s8, 10
	s_add_u32 s12, s6, s9
	v_mov_b32_e32 v167, v164
	s_addc_u32 s13, s7, 0
	s_lshl_b64 s[6:7], s[4:5], 9
	s_add_u32 s6, s20, s6
	v_lshlrev_b32_e32 v162, 2, v167
	s_addc_u32 s7, s21, s7
	v_ashrrev_i32_e32 v163, 31, v162
	v_lshl_add_u64 v[0:1], v[162:163], 1, s[6:7]
	global_load_dwordx2 v[6:7], v[0:1], off
	v_and_b32_e32 v18, 15, v167
	v_ashrrev_i32_e32 v168, 4, v167
	v_and_b32_e32 v160, 3, v18
	v_lshlrev_b32_e32 v160, 8, v160
	v_lshrrev_b32_e32 v4, 3, v18
	v_lshl_or_b32 v160, v4, 6, v160
	v_lshlrev_b32_e32 v4, 3, v168
	v_ashrrev_i32_e32 v5, 31, v4
	v_lshl_add_u64 v[8:9], s[12:13], 0, v[160:161]
	v_lshl_add_u64 v[16:17], v[4:5], 1, v[8:9]
	v_lshl_add_u32 v3, v167, 4, s22
	v_mov_b32_e32 v0, 0
	v_mov_b32_e32 v1, 0
	v_mov_b32_e32 v2, 0
	v_and_b32_e32 v19, 4, v18
	v_cmp_eq_u32_e32 vcc, 0, v19
	s_waitcnt vmcnt(0)
	v_lshlrev_b32_e32 v4, 8, v6
	v_lshlrev_b32_sdwa v5, v165, v6 dst_sel:DWORD dst_unused:UNUSED_PAD src0_sel:DWORD src1_sel:WORD_1
	v_lshlrev_b32_e32 v6, 8, v7
	v_lshlrev_b32_sdwa v7, v165, v7 dst_sel:DWORD dst_unused:UNUSED_PAD src0_sel:DWORD src1_sel:WORD_1
	v_and_b32_e32 v4, 0xffff00, v4
	v_and_b32_e32 v6, 0xffff00, v6
	ds_write_b128 v3, v[4:7]
	v_mov_b32_e32 v3, 0
	s_and_saveexec_b64 s[6:7], vcc
	s_cbranch_execz .LBB0_2939
	global_load_dwordx4 v[0:3], v[16:17], off
.LBB0_2939:
	s_or_b64 exec, exec, s[6:7]
	v_mov_b32_e32 v4, 0
	v_mov_b32_e32 v8, 0
	v_mov_b32_e32 v9, 0
	v_mov_b32_e32 v10, 0
	v_mov_b32_e32 v11, 0
	s_and_saveexec_b64 s[6:7], vcc
	s_cbranch_execz .LBB0_2941
.LBB0_2941:
	s_or_b64 exec, exec, s[6:7]
	v_mov_b32_e32 v5, 0
	v_mov_b32_e32 v6, 0
	v_mov_b32_e32 v7, 0
	s_and_saveexec_b64 s[6:7], vcc
	s_cbranch_execz .LBB0_2943
	global_load_dwordx4 v[4:7], v[16:17], off offset:128

; #define ATT_LOADK(buf, grp) do { _Pragma("unroll") for (int tl = 0; tl < 4; ++tl) { const unsigned ko = li[((grp) * 4 + tl) * 16 + n] + (unsigned)g * 16u; \
;         _Pragma("unroll") for (int kk = 0; kk < 4; ++kk) ka[buf][tl][kk] = *(const bf16x8*)((const char*)Kb + (ko + kk * 64u)); } } while (0)
; __device__ __forceinline__ void attend_one(unsigned char* ws, LAS unsigned char* lds, int wave, int bb, int t, int kvh, int lane) {
;     ...
;     ATT_LOADK(0, 0); ATT_LOADK(1, 1);
;     __builtin_amdgcn_sched_barrier(0);
;     f32x4 S[16];
; #pragma unroll
;     for (int gi = 0; gi < 4; ++gi) {
; #pragma unroll
;         for (int tl = 0; tl < 4; ++tl) { f32x4 a = {0.f, 0.f, 0.f, 0.f};
; #pragma unroll
;             for (int kk = 0; kk < 4; ++kk) a = __builtin_amdgcn_mfma_f32_16x16x32_bf16(ka[gi & 1][tl][kk], qf[kk], a, 0, 0, 0);
;             S[gi * 4 + tl] = a; }
;         __builtin_amdgcn_sched_barrier(0);
;         if (gi + 2 < 4) { ATT_LOADK(gi & 1, gi + 2); __builtin_amdgcn_sched_barrier(0); }
;     }
.LBB0_2945:
	s_or_b64 exec, exec, s[6:7]
	s_waitcnt vmcnt(0) lgkmcnt(0)
	s_lshl_b32 s5, s8, 21
	s_add_u32 s6, s23, s5
	s_addc_u32 s7, s24, 0
	s_add_u32 s14, s16, s5
	s_addc_u32 s15, s17, 0
	v_and_b32_e32 v250, 7, v167
	v_lshl_add_u32 v250, v250, 2, s22
	v_lshrrev_b32_e32 v251, 4, v167
	v_bfe_u32 v252, v167, 3, 1
	v_lshlrev_b32_e32 v251, 4, v251
	v_lshl_or_b32 v251, v252, 6, v251
	ds_read2_b32 v[242:243], v250 offset0:0 offset1:8
	ds_read2_b32 v[244:245], v250 offset0:16 offset1:24
	ds_read2_b32 v[246:247], v250 offset0:32 offset1:40
	ds_read2_b32 v[248:249], v250 offset0:48 offset1:56
	s_waitcnt lgkmcnt(0)
	v_add_u32_e32 v252, v242, v251
	v_add_u32_e32 v253, v243, v251
	global_load_dwordx4 v[20:23], v252, s[6:7]
	global_load_dwordx4 v[24:27], v252, s[6:7] offset:128
	global_load_dwordx4 v[28:31], v253, s[6:7]
	global_load_dwordx4 v[32:35], v253, s[6:7] offset:128
	v_add_u32_e32 v252, v244, v251
	v_add_u32_e32 v253, v245, v251
	global_load_dwordx4 v[36:39], v252, s[6:7]
	global_load_dwordx4 v[40:43], v252, s[6:7] offset:128
	global_load_dwordx4 v[44:47], v253, s[6:7]
	global_load_dwordx4 v[48:51], v253, s[6:7] offset:128
	v_add_u32_e32 v252, v246, v251
	v_add_u32_e32 v253, v247, v251
	global_load_dwordx4 v[52:55], v252, s[6:7]
	global_load_dwordx4 v[56:59], v252, s[6:7] offset:128
	global_load_dwordx4 v[60:63], v253, s[6:7]
	global_load_dwordx4 v[64:67], v253, s[6:7] offset:128
	v_add_u32_e32 v252, v248, v251
	v_add_u32_e32 v253, v249, v251
	global_load_dwordx4 v[68:71], v252, s[6:7]
	global_load_dwordx4 v[72:75], v252, s[6:7] offset:128
	global_load_dwordx4 v[76:79], v253, s[6:7]
	global_load_dwordx4 v[80:83], v253, s[6:7] offset:128
	ds_read2_b32 v[242:243], v250 offset0:64 offset1:72
	ds_read2_b32 v[244:245], v250 offset0:80 offset1:88
	ds_read2_b32 v[246:247], v250 offset0:96 offset1:104
	ds_read2_b32 v[248:249], v250 offset0:112 offset1:120
	s_waitcnt lgkmcnt(0)
	v_add_u32_e32 v252, v242, v251
	v_add_u32_e32 v253, v243, v251
	global_load_dwordx4 v[170:173], v252, s[6:7]
	global_load_dwordx4 v[174:177], v252, s[6:7] offset:128
	global_load_dwordx4 v[178:181], v253, s[6:7]
	global_load_dwordx4 v[182:185], v253, s[6:7] offset:128
	v_add_u32_e32 v252, v244, v251
	v_add_u32_e32 v253, v245, v251
	global_load_dwordx4 v[186:189], v252, s[6:7]
	global_load_dwordx4 v[190:193], v252, s[6:7] offset:128
	global_load_dwordx4 v[194:197], v253, s[6:7]
	global_load_dwordx4 v[198:201], v253, s[6:7] offset:128
	v_add_u32_e32 v252, v246, v251
	v_add_u32_e32 v253, v247, v251
	global_load_dwordx4 v[202:205], v252, s[6:7]
	global_load_dwordx4 v[206:209], v252, s[6:7] offset:128
	global_load_dwordx4 v[210:213], v253, s[6:7]
	global_load_dwordx4 v[214:217], v253, s[6:7] offset:128
	v_add_u32_e32 v252, v248, v251
	v_add_u32_e32 v253, v249, v251
	global_load_dwordx4 v[218:221], v252, s[6:7]
	global_load_dwordx4 v[222:225], v252, s[6:7] offset:128
	global_load_dwordx4 v[226:229], v253, s[6:7]
	global_load_dwordx4 v[230:233], v253, s[6:7] offset:128
	s_waitcnt vmcnt(28)
	v_mfma_f32_16x16x32_bf16 v[148:151], v[20:23], v[0:3], 0
	v_mfma_f32_16x16x32_bf16 v[148:151], v[24:27], v[4:7], v[148:151]
	v_mfma_f32_16x16x32_bf16 v[234:237], v[28:31], v[0:3], 0
	v_mfma_f32_16x16x32_bf16 v[234:237], v[32:35], v[4:7], v[234:237]
	s_waitcnt vmcnt(24)
	v_mfma_f32_16x16x32_bf16 v[136:139], v[36:39], v[0:3], 0
	v_mfma_f32_16x16x32_bf16 v[136:139], v[40:43], v[4:7], v[136:139]
	v_mfma_f32_16x16x32_bf16 v[238:241], v[44:47], v[0:3], 0
	v_mfma_f32_16x16x32_bf16 v[238:241], v[48:51], v[4:7], v[238:241]
	s_nop 3
	v_permlane32_swap_b32_e32 v148, v234
	v_permlane32_swap_b32_e32 v149, v235
	v_permlane32_swap_b32_e32 v150, v236
	v_permlane32_swap_b32_e32 v151, v237
	v_add_f32_dpp v148, v234, v148 row_ror:8 row_mask:0xf bank_mask:0xf
	v_add_f32_dpp v149, v235, v149 row_ror:8 row_mask:0xf bank_mask:0xf
	v_add_f32_dpp v150, v236, v150 row_ror:8 row_mask:0xf bank_mask:0xf
	v_add_f32_dpp v151, v237, v151 row_ror:8 row_mask:0xf bank_mask:0xf
	s_waitcnt vmcnt(20)
	v_mfma_f32_16x16x32_bf16 v[124:127], v[52:55], v[0:3], 0
	v_mfma_f32_16x16x32_bf16 v[124:127], v[56:59], v[4:7], v[124:127]
	v_mfma_f32_16x16x32_bf16 v[234:237], v[60:63], v[0:3], 0
	v_mfma_f32_16x16x32_bf16 v[234:237], v[64:67], v[4:7], v[234:237]
	s_nop 3
	v_permlane32_swap_b32_e32 v136, v238
	v_permlane32_swap_b32_e32 v137, v239
	v_permlane32_swap_b32_e32 v138, v240
	v_permlane32_swap_b32_e32 v139, v241
	v_add_f32_dpp v136, v238, v136 row_ror:8 row_mask:0xf bank_mask:0xf
	v_add_f32_dpp v137, v239, v137 row_ror:8 row_mask:0xf bank_mask:0xf
	v_add_f32_dpp v138, v240, v138 row_ror:8 row_mask:0xf bank_mask:0xf
	v_add_f32_dpp v139, v241, v139 row_ror:8 row_mask:0xf bank_mask:0xf
	s_waitcnt vmcnt(16)
	v_mfma_f32_16x16x32_bf16 v[112:115], v[68:71], v[0:3], 0
	v_mfma_f32_16x16x32_bf16 v[112:115], v[72:75], v[4:7], v[112:115]
	v_mfma_f32_16x16x32_bf16 v[238:241], v[76:79], v[0:3], 0
	v_mfma_f32_16x16x32_bf16 v[238:241], v[80:83], v[4:7], v[238:241]
	s_nop 3
	v_permlane32_swap_b32_e32 v124, v234
	v_permlane32_swap_b32_e32 v125, v235
	v_permlane32_swap_b32_e32 v126, v236
	v_permlane32_swap_b32_e32 v127, v237
	v_add_f32_dpp v124, v234, v124 row_ror:8 row_mask:0xf bank_mask:0xf
	v_add_f32_dpp v125, v235, v125 row_ror:8 row_mask:0xf bank_mask:0xf
	v_add_f32_dpp v126, v236, v126 row_ror:8 row_mask:0xf bank_mask:0xf
	v_add_f32_dpp v127, v237, v127 row_ror:8 row_mask:0xf bank_mask:0xf
	s_nop 7
	v_permlane32_swap_b32_e32 v112, v238
	v_permlane32_swap_b32_e32 v113, v239
	v_permlane32_swap_b32_e32 v114, v240
	v_permlane32_swap_b32_e32 v115, v241
	v_add_f32_dpp v112, v238, v112 row_ror:8 row_mask:0xf bank_mask:0xf
	v_add_f32_dpp v113, v239, v113 row_ror:8 row_mask:0xf bank_mask:0xf
	v_add_f32_dpp v114, v240, v114 row_ror:8 row_mask:0xf bank_mask:0xf
	v_add_f32_dpp v115, v241, v115 row_ror:8 row_mask:0xf bank_mask:0xf
	ds_read2_b32 v[242:243], v250 offset0:128 offset1:136
	ds_read2_b32 v[244:245], v250 offset0:144 offset1:152
	ds_read2_b32 v[246:247], v250 offset0:160 offset1:168
	ds_read2_b32 v[248:249], v250 offset0:176 offset1:184
	s_waitcnt lgkmcnt(0)
; #define ATT_LOADK(buf, grp) do { _Pragma("unroll") for (int tl = 0; tl < 4; ++tl) { const unsigned ko = li[((grp) * 4 + tl) * 16 + n] + (unsigned)g * 16u; \
;         _Pragma("unroll") for (int kk = 0; kk < 4; ++kk) ka[buf][tl][kk] = *(const bf16x8*)((const char*)Kb + (ko + kk * 64u)); } } while (0)
; __device__ __forceinline__ void attend_one(unsigned char* ws, LAS unsigned char* lds, int wave, int bb, int t, int kvh, int lane) {
;     ...
;     ATT_LOADK(0, 0); ATT_LOADK(1, 1);
;     __builtin_amdgcn_sched_barrier(0);
;     f32x4 S[16];
; #pragma unroll
;     for (int gi = 0; gi < 4; ++gi) {
; #pragma unroll
;         for (int tl = 0; tl < 4; ++tl) { f32x4 a = {0.f, 0.f, 0.f, 0.f};
; #pragma unroll
;             for (int kk = 0; kk < 4; ++kk) a = __builtin_amdgcn_mfma_f32_16x16x32_bf16(ka[gi & 1][tl][kk], qf[kk], a, 0, 0, 0);
;             S[gi * 4 + tl] = a; }
;         __builtin_amdgcn_sched_barrier(0);
;         if (gi + 2 < 4) { ATT_LOADK(gi & 1, gi + 2); __builtin_amdgcn_sched_barrier(0); }
;     }
	v_add_u32_e32 v252, v242, v251
	v_add_u32_e32 v253, v243, v251
	global_load_dwordx4 v[20:23], v252, s[6:7]
	global_load_dwordx4 v[24:27], v252, s[6:7] offset:128
	global_load_dwordx4 v[28:31], v253, s[6:7]
	global_load_dwordx4 v[32:35], v253, s[6:7] offset:128
	v_add_u32_e32 v252, v244, v251
	v_add_u32_e32 v253, v245, v251
	global_load_dwordx4 v[36:39], v252, s[6:7]
	global_load_dwordx4 v[40:43], v252, s[6:7] offset:128
	global_load_dwordx4 v[44:47], v253, s[6:7]
	global_load_dwordx4 v[48:51], v253, s[6:7] offset:128
	v_add_u32_e32 v252, v246, v251
	v_add_u32_e32 v253, v247, v251
	global_load_dwordx4 v[52:55], v252, s[6:7]
	global_load_dwordx4 v[56:59], v252, s[6:7] offset:128
	global_load_dwordx4 v[60:63], v253, s[6:7]
	global_load_dwordx4 v[64:67], v253, s[6:7] offset:128
	v_add_u32_e32 v252, v248, v251
	v_add_u32_e32 v253, v249, v251
	global_load_dwordx4 v[68:71], v252, s[6:7]
	global_load_dwordx4 v[72:75], v252, s[6:7] offset:128
	global_load_dwordx4 v[76:79], v253, s[6:7]
	global_load_dwordx4 v[80:83], v253, s[6:7] offset:128
	s_waitcnt vmcnt(28)
	v_mfma_f32_16x16x32_bf16 v[152:155], v[170:173], v[0:3], 0
	v_mfma_f32_16x16x32_bf16 v[152:155], v[174:177], v[4:7], v[152:155]
	v_mfma_f32_16x16x32_bf16 v[234:237], v[178:181], v[0:3], 0
	v_mfma_f32_16x16x32_bf16 v[234:237], v[182:185], v[4:7], v[234:237]
	s_waitcnt vmcnt(24)
	v_mfma_f32_16x16x32_bf16 v[140:143], v[186:189], v[0:3], 0
	v_mfma_f32_16x16x32_bf16 v[140:143], v[190:193], v[4:7], v[140:143]
	v_mfma_f32_16x16x32_bf16 v[238:241], v[194:197], v[0:3], 0
	v_mfma_f32_16x16x32_bf16 v[238:241], v[198:201], v[4:7], v[238:241]
	s_nop 3
	v_permlane32_swap_b32_e32 v152, v234
	v_permlane32_swap_b32_e32 v153, v235
	v_permlane32_swap_b32_e32 v154, v236
	v_permlane32_swap_b32_e32 v155, v237
	v_add_f32_dpp v152, v234, v152 row_ror:8 row_mask:0xf bank_mask:0xf
	v_add_f32_dpp v153, v235, v153 row_ror:8 row_mask:0xf bank_mask:0xf
	v_add_f32_dpp v154, v236, v154 row_ror:8 row_mask:0xf bank_mask:0xf
	v_add_f32_dpp v155, v237, v155 row_ror:8 row_mask:0xf bank_mask:0xf
	s_waitcnt vmcnt(20)
	v_mfma_f32_16x16x32_bf16 v[128:131], v[202:205], v[0:3], 0
	v_mfma_f32_16x16x32_bf16 v[128:131], v[206:209], v[4:7], v[128:131]
	v_mfma_f32_16x16x32_bf16 v[234:237], v[210:213], v[0:3], 0
	v_mfma_f32_16x16x32_bf16 v[234:237], v[214:217], v[4:7], v[234:237]
	s_nop 3
	v_permlane32_swap_b32_e32 v140, v238
	v_permlane32_swap_b32_e32 v141, v239
	v_permlane32_swap_b32_e32 v142, v240
	v_permlane32_swap_b32_e32 v143, v241
	v_add_f32_dpp v140, v238, v140 row_ror:8 row_mask:0xf bank_mask:0xf
	v_add_f32_dpp v141, v239, v141 row_ror:8 row_mask:0xf bank_mask:0xf
	v_add_f32_dpp v142, v240, v142 row_ror:8 row_mask:0xf bank_mask:0xf
	v_add_f32_dpp v143, v241, v143 row_ror:8 row_mask:0xf bank_mask:0xf
	s_waitcnt vmcnt(16)
	v_mfma_f32_16x16x32_bf16 v[116:119], v[218:221], v[0:3], 0
	v_mfma_f32_16x16x32_bf16 v[116:119], v[222:225], v[4:7], v[116:119]
	v_mfma_f32_16x16x32_bf16 v[238:241], v[226:229], v[0:3], 0
	v_mfma_f32_16x16x32_bf16 v[238:241], v[230:233], v[4:7], v[238:241]
	s_nop 3
	v_permlane32_swap_b32_e32 v128, v234
	v_permlane32_swap_b32_e32 v129, v235
	v_permlane32_swap_b32_e32 v130, v236
	v_permlane32_swap_b32_e32 v131, v237
	v_add_f32_dpp v128, v234, v128 row_ror:8 row_mask:0xf bank_mask:0xf
	v_add_f32_dpp v129, v235, v129 row_ror:8 row_mask:0xf bank_mask:0xf
	v_add_f32_dpp v130, v236, v130 row_ror:8 row_mask:0xf bank_mask:0xf
	v_add_f32_dpp v131, v237, v131 row_ror:8 row_mask:0xf bank_mask:0xf
	s_nop 7
	v_permlane32_swap_b32_e32 v116, v238
	v_permlane32_swap_b32_e32 v117, v239
	v_permlane32_swap_b32_e32 v118, v240
	v_permlane32_swap_b32_e32 v119, v241
	v_add_f32_dpp v116, v238, v116 row_ror:8 row_mask:0xf bank_mask:0xf
	v_add_f32_dpp v117, v239, v117 row_ror:8 row_mask:0xf bank_mask:0xf
	v_add_f32_dpp v118, v240, v118 row_ror:8 row_mask:0xf bank_mask:0xf
	v_add_f32_dpp v119, v241, v119 row_ror:8 row_mask:0xf bank_mask:0xf
	ds_read2_b32 v[242:243], v250 offset0:192 offset1:200
	ds_read2_b32 v[244:245], v250 offset0:208 offset1:216
	ds_read2_b32 v[246:247], v250 offset0:224 offset1:232
	ds_read2_b32 v[248:249], v250 offset0:240 offset1:248
	s_waitcnt lgkmcnt(0)
	v_add_u32_e32 v252, v242, v251
	v_add_u32_e32 v253, v243, v251
	global_load_dwordx4 v[170:173], v252, s[6:7]
	global_load_dwordx4 v[174:177], v252, s[6:7] offset:128
	global_load_dwordx4 v[178:181], v253, s[6:7]
	global_load_dwordx4 v[182:185], v253, s[6:7] offset:128
	v_add_u32_e32 v252, v244, v251
	v_add_u32_e32 v253, v245, v251
	global_load_dwordx4 v[186:189], v252, s[6:7]
	global_load_dwordx4 v[190:193], v252, s[6:7] offset:128
	global_load_dwordx4 v[194:197], v253, s[6:7]
	global_load_dwordx4 v[198:201], v253, s[6:7] offset:128
	v_add_u32_e32 v252, v246, v251
	v_add_u32_e32 v253, v247, v251
	global_load_dwordx4 v[202:205], v252, s[6:7]
	global_load_dwordx4 v[206:209], v252, s[6:7] offset:128
	global_load_dwordx4 v[210:213], v253, s[6:7]
	global_load_dwordx4 v[214:217], v253, s[6:7] offset:128
	v_add_u32_e32 v252, v248, v251
	v_add_u32_e32 v253, v249, v251
	global_load_dwordx4 v[218:221], v252, s[6:7]
	global_load_dwordx4 v[222:225], v252, s[6:7] offset:128
	global_load_dwordx4 v[226:229], v253, s[6:7]
	global_load_dwordx4 v[230:233], v253, s[6:7] offset:128
	s_waitcnt vmcnt(28)
	v_mfma_f32_16x16x32_bf16 v[156:159], v[20:23], v[0:3], 0
	v_mfma_f32_16x16x32_bf16 v[156:159], v[24:27], v[4:7], v[156:159]
	v_mfma_f32_16x16x32_bf16 v[234:237], v[28:31], v[0:3], 0
	v_mfma_f32_16x16x32_bf16 v[234:237], v[32:35], v[4:7], v[234:237]
	s_waitcnt vmcnt(24)
; #define ATT_LOADK(buf, grp) do { _Pragma("unroll") for (int tl = 0; tl < 4; ++tl) { const unsigned ko = li[((grp) * 4 + tl) * 16 + n] + (unsigned)g * 16u; \
;         _Pragma("unroll") for (int kk = 0; kk < 4; ++kk) ka[buf][tl][kk] = *(const bf16x8*)((const char*)Kb + (ko + kk * 64u)); } } while (0)
; #define ATT_LOADV(buf, ks) do { const u32x4 i0 = *(const LAS u32x4*)(li + (ks) * 32 + 4 * g), i1 = *(const LAS u32x4*)(li + (ks) * 32 + 16 + 4 * g); \
;         const unsigned kidx[8] = {i0.x, i0.y, i0.z, i0.w, i1.x, i1.y, i1.z, i1.w}; \
;         _Pragma("unroll") for (int jj = 0; jj < 8; ++jj) R[buf][jj] = *(const u32x4*)((const char*)Vb + (kidx[jj] + (unsigned)n * 16u)); } while (0)
; __device__ __forceinline__ void attend_one(unsigned char* ws, LAS unsigned char* lds, int wave, int bb, int t, int kvh, int lane) {
;     ...
; #pragma unroll
;     for (int gi = 0; gi < 4; ++gi) {
; #pragma unroll
;         for (int tl = 0; tl < 4; ++tl) { f32x4 a = {0.f, 0.f, 0.f, 0.f};
; #pragma unroll
;             for (int kk = 0; kk < 4; ++kk) a = __builtin_amdgcn_mfma_f32_16x16x32_bf16(ka[gi & 1][tl][kk], qf[kk], a, 0, 0, 0);
;             S[gi * 4 + tl] = a; }
;         __builtin_amdgcn_sched_barrier(0);
;         if (gi + 2 < 4) { ATT_LOADK(gi & 1, gi + 2); __builtin_amdgcn_sched_barrier(0); }
;     }
;     ...
;     u32x4 R[3][8];
;     ...
;     ATT_LOADV(0, 0); ATT_LOADV(1, 1); ATT_LOADV(2, 2);
	v_mfma_f32_16x16x32_bf16 v[144:147], v[36:39], v[0:3], 0
	v_mfma_f32_16x16x32_bf16 v[144:147], v[40:43], v[4:7], v[144:147]
	v_mfma_f32_16x16x32_bf16 v[238:241], v[44:47], v[0:3], 0
	v_mfma_f32_16x16x32_bf16 v[238:241], v[48:51], v[4:7], v[238:241]
	s_nop 3
	v_permlane32_swap_b32_e32 v156, v234
	v_permlane32_swap_b32_e32 v157, v235
	v_permlane32_swap_b32_e32 v158, v236
	v_permlane32_swap_b32_e32 v159, v237
	v_add_f32_dpp v156, v234, v156 row_ror:8 row_mask:0xf bank_mask:0xf
	v_add_f32_dpp v157, v235, v157 row_ror:8 row_mask:0xf bank_mask:0xf
	v_add_f32_dpp v158, v236, v158 row_ror:8 row_mask:0xf bank_mask:0xf
	v_add_f32_dpp v159, v237, v159 row_ror:8 row_mask:0xf bank_mask:0xf
	s_waitcnt vmcnt(20)
	v_mfma_f32_16x16x32_bf16 v[132:135], v[52:55], v[0:3], 0
	v_mfma_f32_16x16x32_bf16 v[132:135], v[56:59], v[4:7], v[132:135]
	v_mfma_f32_16x16x32_bf16 v[234:237], v[60:63], v[0:3], 0
	v_mfma_f32_16x16x32_bf16 v[234:237], v[64:67], v[4:7], v[234:237]
	s_nop 3
	v_permlane32_swap_b32_e32 v144, v238
	v_permlane32_swap_b32_e32 v145, v239
	v_permlane32_swap_b32_e32 v146, v240
	v_permlane32_swap_b32_e32 v147, v241
	v_add_f32_dpp v144, v238, v144 row_ror:8 row_mask:0xf bank_mask:0xf
	v_add_f32_dpp v145, v239, v145 row_ror:8 row_mask:0xf bank_mask:0xf
	v_add_f32_dpp v146, v240, v146 row_ror:8 row_mask:0xf bank_mask:0xf
	v_add_f32_dpp v147, v241, v147 row_ror:8 row_mask:0xf bank_mask:0xf
	s_waitcnt vmcnt(16)
	v_mfma_f32_16x16x32_bf16 v[120:123], v[68:71], v[0:3], 0
	v_mfma_f32_16x16x32_bf16 v[120:123], v[72:75], v[4:7], v[120:123]
	v_mfma_f32_16x16x32_bf16 v[238:241], v[76:79], v[0:3], 0
	v_mfma_f32_16x16x32_bf16 v[238:241], v[80:83], v[4:7], v[238:241]
	s_nop 3
	v_permlane32_swap_b32_e32 v132, v234
	v_permlane32_swap_b32_e32 v133, v235
	v_permlane32_swap_b32_e32 v134, v236
	v_permlane32_swap_b32_e32 v135, v237
	v_add_f32_dpp v132, v234, v132 row_ror:8 row_mask:0xf bank_mask:0xf
	v_add_f32_dpp v133, v235, v133 row_ror:8 row_mask:0xf bank_mask:0xf
	v_add_f32_dpp v134, v236, v134 row_ror:8 row_mask:0xf bank_mask:0xf
	v_add_f32_dpp v135, v237, v135 row_ror:8 row_mask:0xf bank_mask:0xf
	s_nop 7
	v_permlane32_swap_b32_e32 v120, v238
	v_permlane32_swap_b32_e32 v121, v239
	v_permlane32_swap_b32_e32 v122, v240
	v_permlane32_swap_b32_e32 v123, v241
	v_add_f32_dpp v120, v238, v120 row_ror:8 row_mask:0xf bank_mask:0xf
	v_add_f32_dpp v121, v239, v121 row_ror:8 row_mask:0xf bank_mask:0xf
	v_add_f32_dpp v122, v240, v122 row_ror:8 row_mask:0xf bank_mask:0xf
	v_add_f32_dpp v123, v241, v123 row_ror:8 row_mask:0xf bank_mask:0xf
	s_waitcnt vmcnt(12)
	v_mfma_f32_16x16x32_bf16 v[108:111], v[170:173], v[0:3], 0
	v_mfma_f32_16x16x32_bf16 v[108:111], v[174:177], v[4:7], v[108:111]
	v_mfma_f32_16x16x32_bf16 v[234:237], v[178:181], v[0:3], 0
	v_mfma_f32_16x16x32_bf16 v[234:237], v[182:185], v[4:7], v[234:237]
	s_waitcnt vmcnt(8)
	v_mfma_f32_16x16x32_bf16 v[104:107], v[186:189], v[0:3], 0
	v_mfma_f32_16x16x32_bf16 v[104:107], v[190:193], v[4:7], v[104:107]
	v_mfma_f32_16x16x32_bf16 v[238:241], v[194:197], v[0:3], 0
	v_mfma_f32_16x16x32_bf16 v[238:241], v[198:201], v[4:7], v[238:241]
	s_nop 3
	v_permlane32_swap_b32_e32 v108, v234
	v_permlane32_swap_b32_e32 v109, v235
	v_permlane32_swap_b32_e32 v110, v236
	v_permlane32_swap_b32_e32 v111, v237
	v_add_f32_dpp v108, v234, v108 row_ror:8 row_mask:0xf bank_mask:0xf
	v_add_f32_dpp v109, v235, v109 row_ror:8 row_mask:0xf bank_mask:0xf
	v_add_f32_dpp v110, v236, v110 row_ror:8 row_mask:0xf bank_mask:0xf
	v_add_f32_dpp v111, v237, v111 row_ror:8 row_mask:0xf bank_mask:0xf
	s_waitcnt vmcnt(4)
	v_mfma_f32_16x16x32_bf16 v[100:103], v[202:205], v[0:3], 0
	v_mfma_f32_16x16x32_bf16 v[100:103], v[206:209], v[4:7], v[100:103]
	v_mfma_f32_16x16x32_bf16 v[234:237], v[210:213], v[0:3], 0
	v_mfma_f32_16x16x32_bf16 v[234:237], v[214:217], v[4:7], v[234:237]
	s_nop 3
	v_permlane32_swap_b32_e32 v104, v238
	v_permlane32_swap_b32_e32 v105, v239
	v_permlane32_swap_b32_e32 v106, v240
	v_permlane32_swap_b32_e32 v107, v241
	v_add_f32_dpp v104, v238, v104 row_ror:8 row_mask:0xf bank_mask:0xf
	v_add_f32_dpp v105, v239, v105 row_ror:8 row_mask:0xf bank_mask:0xf
	v_add_f32_dpp v106, v240, v106 row_ror:8 row_mask:0xf bank_mask:0xf
	v_add_f32_dpp v107, v241, v107 row_ror:8 row_mask:0xf bank_mask:0xf
	s_waitcnt vmcnt(0)
	v_mfma_f32_16x16x32_bf16 v[96:99], v[218:221], v[0:3], 0
	v_mfma_f32_16x16x32_bf16 v[96:99], v[222:225], v[4:7], v[96:99]
	v_mfma_f32_16x16x32_bf16 v[238:241], v[226:229], v[0:3], 0
	v_mfma_f32_16x16x32_bf16 v[238:241], v[230:233], v[4:7], v[238:241]
	s_nop 3
	v_permlane32_swap_b32_e32 v100, v234
	v_permlane32_swap_b32_e32 v101, v235
	v_permlane32_swap_b32_e32 v102, v236
	v_permlane32_swap_b32_e32 v103, v237
	v_add_f32_dpp v100, v234, v100 row_ror:8 row_mask:0xf bank_mask:0xf
	v_add_f32_dpp v101, v235, v101 row_ror:8 row_mask:0xf bank_mask:0xf
	v_add_f32_dpp v102, v236, v102 row_ror:8 row_mask:0xf bank_mask:0xf
	v_add_f32_dpp v103, v237, v103 row_ror:8 row_mask:0xf bank_mask:0xf
	s_nop 7
	v_permlane32_swap_b32_e32 v96, v238
	v_permlane32_swap_b32_e32 v97, v239
	v_permlane32_swap_b32_e32 v98, v240
	v_permlane32_swap_b32_e32 v99, v241
	v_add_f32_dpp v96, v238, v96 row_ror:8 row_mask:0xf bank_mask:0xf
	v_add_f32_dpp v97, v239, v97 row_ror:8 row_mask:0xf bank_mask:0xf
	v_add_f32_dpp v98, v240, v98 row_ror:8 row_mask:0xf bank_mask:0xf
	v_add_f32_dpp v99, v241, v99 row_ror:8 row_mask:0xf bank_mask:0xf
	v_lshl_add_u32 v163, v168, 4, s22
	s_nop 3
	ds_read_b128 v[0:3], v163
	ds_read_b128 v[4:7], v163 offset:64
	v_lshlrev_b32_e32 v160, 4, v18
	s_waitcnt lgkmcnt(1)
; #define ATT_LOADV(buf, ks) do { const u32x4 i0 = *(const LAS u32x4*)(li + (ks) * 32 + 4 * g), i1 = *(const LAS u32x4*)(li + (ks) * 32 + 16 + 4 * g); \
;         const unsigned kidx[8] = {i0.x, i0.y, i0.z, i0.w, i1.x, i1.y, i1.z, i1.w}; \
;         _Pragma("unroll") for (int jj = 0; jj < 8; ++jj) R[buf][jj] = *(const u32x4*)((const char*)Vb + (kidx[jj] + (unsigned)n * 16u)); } while (0)
; __device__ __forceinline__ void attend_one(unsigned char* ws, LAS unsigned char* lds, int wave, int bb, int t, int kvh, int lane) {
;     ...
;     ATT_LOADV(0, 0); ATT_LOADV(1, 1); ATT_LOADV(2, 2);
	v_add_u32_e32 v0, v0, v160
	v_add_u32_e32 v1, v1, v160
	global_load_dwordx4 v[80:83], v0, s[14:15]
	global_load_dwordx4 v[84:87], v1, s[14:15]
	v_add_u32_e32 v0, v2, v160
	v_add_u32_e32 v1, v3, v160
	global_load_dwordx4 v[64:67], v0, s[14:15]
	global_load_dwordx4 v[68:71], v1, s[14:15]
	s_waitcnt lgkmcnt(0)
	v_add_u32_e32 v0, v4, v160
	v_add_u32_e32 v1, v5, v160
	global_load_dwordx4 v[72:75], v0, s[14:15]
	global_load_dwordx4 v[76:79], v1, s[14:15]
	ds_read_b128 v[0:3], v163 offset:128
	v_add_u32_e32 v4, v6, v160
	v_add_u32_e32 v5, v7, v160
	global_load_dwordx4 v[88:91], v4, s[14:15]
	global_load_dwordx4 v[92:95], v5, s[14:15]
	ds_read_b128 v[4:7], v163 offset:192
	s_waitcnt lgkmcnt(1)
	v_add_u32_e32 v0, v0, v160
	v_add_u32_e32 v1, v1, v160
	global_load_dwordx4 v[48:51], v0, s[14:15]
	global_load_dwordx4 v[52:55], v1, s[14:15]
	v_add_u32_e32 v0, v2, v160
	v_add_u32_e32 v1, v3, v160
	global_load_dwordx4 v[32:35], v0, s[14:15]
	global_load_dwordx4 v[36:39], v1, s[14:15]
	s_waitcnt lgkmcnt(0)
	v_add_u32_e32 v0, v4, v160
	v_add_u32_e32 v1, v5, v160
	global_load_dwordx4 v[40:43], v0, s[14:15]
	global_load_dwordx4 v[44:47], v1, s[14:15]
	v_add_u32_e32 v4, v6, v160
	ds_read_b128 v[0:3], v163 offset:256
	v_add_u32_e32 v5, v7, v160
	global_load_dwordx4 v[56:59], v4, s[14:15]
	global_load_dwordx4 v[60:63], v5, s[14:15]
	ds_read_b128 v[14:17], v163 offset:320
	s_waitcnt lgkmcnt(1)
	v_add_u32_e32 v0, v0, v160
	v_add_u32_e32 v1, v1, v160
	global_load_dwordx4 v[24:27], v0, s[14:15]
	global_load_dwordx4 v[28:31], v1, s[14:15]
	v_add_u32_e32 v0, v2, v160
	v_add_u32_e32 v4, v3, v160
	s_waitcnt lgkmcnt(0)
	v_add_u32_e32 v8, v14, v160
	v_add_u32_e32 v12, v15, v160
	v_add_u32_e32 v16, v16, v160
	v_add_u32_e32 v20, v17, v160
	global_load_dwordx4 v[0:3], v0, s[14:15]
	s_nop 0
	global_load_dwordx4 v[4:7], v4, s[14:15]
	s_nop 0
	global_load_dwordx4 v[8:11], v8, s[14:15]
	s_nop 0
	global_load_dwordx4 v[12:15], v12, s[14:15]
	s_nop 0
	global_load_dwordx4 v[16:19], v16, s[14:15]
	s_nop 0
	global_load_dwordx4 v[20:23], v20, s[14:15]
	s_cmpk_gt_i32 s4, 0xfe
	s_cbranch_scc1 .LBB0_2947
; __device__ __forceinline__ void attend_one(unsigned char* ws, LAS unsigned char* lds, int wave, int bb, int t, int kvh, int lane) {
;     ...
;     if (cnt < 256) {
; #pragma unroll
;         for (int kt = 0; kt < 16; ++kt)
; #pragma unroll
;             for (int j = 0; j < 4; ++j) if (4 * g + j >= cnt - kt * 16) S[kt][j] = -3.0e38f;
;     }
	v_lshlrev_b32_e32 v169, 2, v168
	s_min_i32 s29, s4, 0xff
	v_mov_b32_e32 v168, s26
	v_cmp_lt_i32_e32 vcc, s29, v169
	v_or_b32_e32 v171, 3, v169
	v_or_b32_e32 v170, 1, v169
	v_cndmask_b32_e32 v168, v148, v168, vcc
	v_cmp_gt_i32_e32 vcc, s29, v169
	s_add_i32 s8, s29, -15
	v_cmp_gt_i32_e64 s[4:5], s8, v170
	v_cndmask_b32_e32 v148, v168, v148, vcc
	v_or_b32_e32 v168, 2, v169
	v_cndmask_b32_e32 v149, v166, v149, vcc
	v_cmp_ge_i32_e32 vcc, s29, v168
	v_cmp_gt_i32_e64 s[6:7], s8, v168
	s_nop 0
	v_cndmask_b32_e32 v150, v166, v150, vcc
	v_cmp_ge_i32_e32 vcc, s29, v171
	s_nop 1
	v_cndmask_b32_e32 v151, v166, v151, vcc
	v_cmp_gt_i32_e32 vcc, s8, v169
	v_cmp_gt_i32_e64 s[8:9], s8, v171
	s_or_b64 s[6:7], s[8:9], s[6:7]
	s_or_b64 s[4:5], s[6:7], s[4:5]
	v_cndmask_b32_e64 v139, v166, v139, s[8:9]
	s_or_b64 vcc, s[4:5], vcc
	s_sub_i32 s8, s29, 31
	v_cndmask_b32_e64 v138, v166, v138, s[6:7]
	v_cndmask_b32_e64 v137, v166, v137, s[4:5]
	v_cndmask_b32_e32 v136, v166, v136, vcc
	v_cmp_gt_i32_e32 vcc, s8, v169
	v_cmp_gt_i32_e64 s[4:5], s8, v170
	v_cmp_gt_i32_e64 s[6:7], s8, v168
	v_cmp_gt_i32_e64 s[8:9], s8, v171
	s_or_b64 s[6:7], s[8:9], s[6:7]
	s_or_b64 s[4:5], s[6:7], s[4:5]
	v_cndmask_b32_e64 v127, v166, v127, s[8:9]
	s_or_b64 vcc, s[4:5], vcc
	s_sub_i32 s8, s29, 47
	v_cndmask_b32_e64 v126, v166, v126, s[6:7]
	v_cndmask_b32_e64 v125, v166, v125, s[4:5]
	v_cndmask_b32_e32 v124, v166, v124, vcc
	v_cmp_gt_i32_e32 vcc, s8, v169
	v_cmp_gt_i32_e64 s[4:5], s8, v170
	v_cmp_gt_i32_e64 s[6:7], s8, v168
	v_cmp_gt_i32_e64 s[8:9], s8, v171
	s_or_b64 s[6:7], s[8:9], s[6:7]
	s_or_b64 s[4:5], s[6:7], s[4:5]
	v_cndmask_b32_e64 v115, v166, v115, s[8:9]
	s_or_b64 vcc, s[4:5], vcc
	s_sub_i32 s8, s29, 63
	v_cndmask_b32_e64 v114, v166, v114, s[6:7]
	v_cndmask_b32_e64 v113, v166, v113, s[4:5]
	v_cndmask_b32_e32 v112, v166, v112, vcc
	v_cmp_gt_i32_e32 vcc, s8, v169
	v_cmp_gt_i32_e64 s[4:5], s8, v170
	v_cmp_gt_i32_e64 s[6:7], s8, v168
	v_cmp_gt_i32_e64 s[8:9], s8, v171
	s_or_b64 s[6:7], s[8:9], s[6:7]
	s_or_b64 s[4:5], s[6:7], s[4:5]
	v_cndmask_b32_e64 v155, v166, v155, s[8:9]
	s_or_b64 vcc, s[4:5], vcc
	s_add_i32 s8, s29, 0xffffffb1
	v_cndmask_b32_e64 v154, v166, v154, s[6:7]
	v_cndmask_b32_e64 v153, v166, v153, s[4:5]
	v_cndmask_b32_e32 v152, v166, v152, vcc
	v_cmp_gt_i32_e32 vcc, s8, v169
	v_cmp_gt_i32_e64 s[4:5], s8, v170
	v_cmp_gt_i32_e64 s[6:7], s8, v168
	v_cmp_gt_i32_e64 s[8:9], s8, v171
	s_or_b64 s[6:7], s[8:9], s[6:7]
	s_or_b64 s[4:5], s[6:7], s[4:5]
	v_cndmask_b32_e64 v143, v166, v143, s[8:9]
	s_or_b64 vcc, s[4:5], vcc
	s_add_i32 s8, s29, 0xffffffa1
	v_cndmask_b32_e64 v142, v166, v142, s[6:7]
	v_cndmask_b32_e64 v141, v166, v141, s[4:5]
	v_cndmask_b32_e32 v140, v166, v140, vcc
	v_cmp_gt_i32_e32 vcc, s8, v169
	v_cmp_gt_i32_e64 s[4:5], s8, v170
	v_cmp_gt_i32_e64 s[6:7], s8, v168
	v_cmp_gt_i32_e64 s[8:9], s8, v171
	s_or_b64 s[6:7], s[8:9], s[6:7]
	s_or_b64 s[4:5], s[6:7], s[4:5]
	v_cndmask_b32_e64 v131, v166, v131, s[8:9]
	s_or_b64 vcc, s[4:5], vcc
	s_add_i32 s8, s29, 0xffffff91
	v_cndmask_b32_e64 v130, v166, v130, s[6:7]
	v_cndmask_b32_e64 v129, v166, v129, s[4:5]
	v_cndmask_b32_e32 v128, v166, v128, vcc
	v_cmp_gt_i32_e32 vcc, s8, v169
	v_cmp_gt_i32_e64 s[4:5], s8, v170
	v_cmp_gt_i32_e64 s[6:7], s8, v168
	v_cmp_gt_i32_e64 s[8:9], s8, v171
	s_or_b64 s[6:7], s[8:9], s[6:7]
	s_or_b64 s[4:5], s[6:7], s[4:5]
	v_cndmask_b32_e64 v119, v166, v119, s[8:9]
	s_or_b64 vcc, s[4:5], vcc
	s_add_i32 s8, s29, 0xffffff81
	v_cndmask_b32_e64 v118, v166, v118, s[6:7]
	v_cndmask_b32_e64 v117, v166, v117, s[4:5]
	v_cndmask_b32_e32 v116, v166, v116, vcc
	v_cmp_gt_i32_e32 vcc, s8, v169
	v_cmp_gt_i32_e64 s[4:5], s8, v170
	v_cmp_gt_i32_e64 s[6:7], s8, v168
	v_cmp_gt_i32_e64 s[8:9], s8, v171
	s_or_b64 s[6:7], s[8:9], s[6:7]
	s_or_b64 s[4:5], s[6:7], s[4:5]
	v_cndmask_b32_e64 v159, v166, v159, s[8:9]
	s_or_b64 vcc, s[4:5], vcc
	s_add_i32 s8, s29, 0xffffff71
	v_cndmask_b32_e64 v158, v166, v158, s[6:7]
	v_cndmask_b32_e64 v157, v166, v157, s[4:5]
	v_cndmask_b32_e32 v156, v166, v156, vcc
	v_cmp_gt_i32_e32 vcc, s8, v169
	v_cmp_gt_i32_e64 s[4:5], s8, v170
	v_cmp_gt_i32_e64 s[6:7], s8, v168
	v_cmp_gt_i32_e64 s[8:9], s8, v171
	s_or_b64 s[6:7], s[8:9], s[6:7]
	s_or_b64 s[4:5], s[6:7], s[4:5]
	v_cndmask_b32_e64 v147, v166, v147, s[8:9]
	s_or_b64 vcc, s[4:5], vcc
	s_add_i32 s8, s29, 0xffffff61
	v_cndmask_b32_e64 v146, v166, v146, s[6:7]
	v_cndmask_b32_e64 v145, v166, v145, s[4:5]
	v_cndmask_b32_e32 v144, v166, v144, vcc
	v_cmp_gt_i32_e32 vcc, s8, v169
	v_cmp_gt_i32_e64 s[4:5], s8, v170
	v_cmp_gt_i32_e64 s[6:7], s8, v168
	v_cmp_gt_i32_e64 s[8:9], s8, v171
	s_or_b64 s[6:7], s[8:9], s[6:7]
	s_or_b64 s[4:5], s[6:7], s[4:5]
	v_cndmask_b32_e64 v135, v166, v135, s[8:9]
	s_or_b64 vcc, s[4:5], vcc
	s_add_i32 s8, s29, 0xffffff51
	v_cndmask_b32_e64 v134, v166, v134, s[6:7]
	v_cndmask_b32_e64 v133, v166, v133, s[4:5]
	v_cndmask_b32_e32 v132, v166, v132, vcc
	v_cmp_gt_i32_e32 vcc, s8, v169
	v_cmp_gt_i32_e64 s[4:5], s8, v170
	v_cmp_gt_i32_e64 s[6:7], s8, v168
	v_cmp_gt_i32_e64 s[8:9], s8, v171
	s_or_b64 s[6:7], s[8:9], s[6:7]
	s_or_b64 s[4:5], s[6:7], s[4:5]
	v_cndmask_b32_e64 v123, v166, v123, s[8:9]
	s_or_b64 vcc, s[4:5], vcc
	s_add_i32 s8, s29, 0xffffff41
	v_cndmask_b32_e64 v122, v166, v122, s[6:7]
	v_cndmask_b32_e64 v121, v166, v121, s[4:5]
	v_cndmask_b32_e32 v120, v166, v120, vcc
	v_cmp_gt_i32_e32 vcc, s8, v169
	v_cmp_gt_i32_e64 s[4:5], s8, v170
	v_cmp_gt_i32_e64 s[6:7], s8, v168
	v_cmp_gt_i32_e64 s[8:9], s8, v171
	s_or_b64 s[6:7], s[8:9], s[6:7]
	s_or_b64 s[4:5], s[6:7], s[4:5]
	v_cndmask_b32_e64 v111, v166, v111, s[8:9]
	s_or_b64 vcc, s[4:5], vcc
	s_add_i32 s8, s29, 0xffffff31
	v_cndmask_b32_e64 v110, v166, v110, s[6:7]
	v_cndmask_b32_e64 v109, v166, v109, s[4:5]
	v_cndmask_b32_e32 v108, v166, v108, vcc
	v_cmp_gt_i32_e32 vcc, s8, v169
	v_cmp_gt_i32_e64 s[4:5], s8, v170
	v_cmp_gt_i32_e64 s[6:7], s8, v168
	v_cmp_gt_i32_e64 s[8:9], s8, v171
	s_or_b64 s[6:7], s[8:9], s[6:7]
	s_or_b64 s[4:5], s[6:7], s[4:5]
	v_cndmask_b32_e64 v107, v166, v107, s[8:9]
	s_or_b64 vcc, s[4:5], vcc
	s_add_i32 s8, s29, 0xffffff21
	v_cndmask_b32_e64 v106, v166, v106, s[6:7]
	v_cndmask_b32_e64 v105, v166, v105, s[4:5]
	v_cndmask_b32_e32 v104, v166, v104, vcc
	v_cmp_gt_i32_e32 vcc, s8, v169
	v_cmp_gt_i32_e64 s[4:5], s8, v170
	v_cmp_gt_i32_e64 s[6:7], s8, v168
	v_cmp_gt_i32_e64 s[8:9], s8, v171
	s_or_b64 s[6:7], s[8:9], s[6:7]
	s_addk_i32 s29, 0xff11
	v_cndmask_b32_e64 v103, v166, v103, s[8:9]
	v_cndmask_b32_e64 v102, v166, v102, s[6:7]
	s_or_b64 s[4:5], s[6:7], s[4:5]
	v_cmp_gt_i32_e64 s[6:7], s29, v168
	v_cmp_gt_i32_e64 s[8:9], s29, v171
	v_cndmask_b32_e64 v101, v166, v101, s[4:5]
	s_or_b64 vcc, s[4:5], vcc
	v_cmp_gt_i32_e64 s[4:5], s29, v170
	s_or_b64 s[6:7], s[8:9], s[6:7]
	v_cndmask_b32_e32 v100, v166, v100, vcc
	v_cmp_gt_i32_e32 vcc, s29, v169
	s_or_b64 s[4:5], s[6:7], s[4:5]
	s_or_b64 vcc, s[4:5], vcc
	v_cndmask_b32_e64 v99, v166, v99, s[8:9]
	v_cndmask_b32_e64 v98, v166, v98, s[6:7]
	v_cndmask_b32_e64 v97, v166, v97, s[4:5]
	v_cndmask_b32_e32 v96, v166, v96, vcc

; #define LAS __attribute__((address_space(3)))
; __device__ __forceinline__ void attend_one(unsigned char* ws, LAS unsigned char* lds, int wave, int bb, int t, int kvh, int lane) {
;     ...
;     bf16_t* qrow = (bf16_t*)(ws + WS_DQ) + (size_t)(bb * 8192 + t) * 2048 + kvh * 512;
;     const unsigned short* ix = (const unsigned short*)(ws + WS_IDX) + (size_t)(bb * 8192 + t) * 256;
;     const int cnt = t < 255 ? t + 1 : 256;
;     LAS unsigned* li = (LAS unsigned*)(lds + wave * 1024);
;     { const u32x2 iw = *(const u32x2*)(ix + lane * 4); *(LAS u32x4*)(li + lane * 4) = (u32x4){(iw.x & 0xffffu) << 8, (iw.x >> 16) << 8, (iw.y & 0xffffu) << 8, (iw.y >> 16) << 8}; }
;     bf16x8 qf[4];
; #pragma unroll
;     for (int kk = 0; kk < 4; ++kk) { qf[kk] = (bf16x8){0, 0, 0, 0, 0, 0, 0, 0}; if (n < 4) qf[kk] = *(const bf16x8*)(qrow + n * 128 + kk * 32 + g * 8); }
;     asm volatile("s_waitcnt vmcnt(0) lgkmcnt(0)" ::: "memory");
.LBB0_4757:
	s_ashr_i32 s6, s0, 2
	s_and_b64 s[4:5], s[12:13], exec
	s_cselect_b32 s4, s1, s0
	s_cselect_b32 s6, s27, s6
	s_and_b32 s7, s4, 3
	s_add_i32 s4, s6, 0x2000
	s_ashr_i32 s5, s4, 31
	s_lshl_b64 s[8:9], s[4:5], 12
	s_add_u32 s8, s20, s8
	s_addc_u32 s9, s21, s9
	s_lshl_b32 s14, s7, 10
	s_add_u32 s14, s8, s14
	v_mov_b32_e32 v167, v164
	s_addc_u32 s15, s9, 0
	s_lshl_b64 s[4:5], s[4:5], 9
	s_add_u32 s4, s22, s4
	v_lshlrev_b32_e32 v162, 2, v167
	s_addc_u32 s5, s23, s5
	v_ashrrev_i32_e32 v163, 31, v162
	v_lshl_add_u64 v[0:1], v[162:163], 1, s[4:5]
	global_load_dwordx2 v[6:7], v[0:1], off
	v_and_b32_e32 v18, 15, v167
	v_ashrrev_i32_e32 v168, 4, v167
	v_and_b32_e32 v160, 3, v18
	v_lshlrev_b32_e32 v160, 8, v160
	v_lshrrev_b32_e32 v4, 3, v18
	v_lshl_or_b32 v160, v4, 6, v160
	v_lshlrev_b32_e32 v4, 3, v168
	v_ashrrev_i32_e32 v5, 31, v4
	v_lshl_add_u64 v[8:9], s[14:15], 0, v[160:161]
	v_lshl_add_u64 v[16:17], v[4:5], 1, v[8:9]
	v_lshl_add_u32 v3, v167, 4, s24
	v_mov_b32_e32 v0, 0
	v_mov_b32_e32 v1, 0
	v_mov_b32_e32 v2, 0
	v_and_b32_e32 v19, 4, v18
	v_cmp_eq_u32_e32 vcc, 0, v19
	s_waitcnt vmcnt(0)
	v_lshlrev_b32_e32 v4, 8, v6
	v_lshlrev_b32_sdwa v5, v165, v6 dst_sel:DWORD dst_unused:UNUSED_PAD src0_sel:DWORD src1_sel:WORD_1
	v_lshlrev_b32_e32 v6, 8, v7
	v_lshlrev_b32_sdwa v7, v165, v7 dst_sel:DWORD dst_unused:UNUSED_PAD src0_sel:DWORD src1_sel:WORD_1
	v_and_b32_e32 v4, 0xffff00, v4
	v_and_b32_e32 v6, 0xffff00, v6
	ds_write_b128 v3, v[4:7]
	v_mov_b32_e32 v3, 0
	s_and_saveexec_b64 s[4:5], vcc
	s_cbranch_execz .LBB0_4759
	global_load_dwordx4 v[0:3], v[16:17], off
.LBB0_4759:
	s_or_b64 exec, exec, s[4:5]
	v_mov_b32_e32 v4, 0
	v_mov_b32_e32 v8, 0
	v_mov_b32_e32 v9, 0
	v_mov_b32_e32 v10, 0
	v_mov_b32_e32 v11, 0
	s_and_saveexec_b64 s[4:5], vcc
	s_cbranch_execz .LBB0_4761
.LBB0_4761:
	s_or_b64 exec, exec, s[4:5]
	v_mov_b32_e32 v5, 0
	v_mov_b32_e32 v6, 0
	v_mov_b32_e32 v7, 0
	s_and_saveexec_b64 s[4:5], vcc
	s_cbranch_execz .LBB0_4763
	global_load_dwordx4 v[4:7], v[16:17], off offset:128

; #define ATT_LOADK(buf, grp) do { _Pragma("unroll") for (int tl = 0; tl < 4; ++tl) { const unsigned ko = li[((grp) * 4 + tl) * 16 + n] + (unsigned)g * 16u; \
;         _Pragma("unroll") for (int kk = 0; kk < 4; ++kk) ka[buf][tl][kk] = *(const bf16x8*)((const char*)Kb + (ko + kk * 64u)); } } while (0)
; __device__ __forceinline__ void attend_one(unsigned char* ws, LAS unsigned char* lds, int wave, int bb, int t, int kvh, int lane) {
;     ...
;     ATT_LOADK(0, 0); ATT_LOADK(1, 1);
;     __builtin_amdgcn_sched_barrier(0);
;     f32x4 S[16];
; #pragma unroll
;     for (int gi = 0; gi < 4; ++gi) {
; #pragma unroll
;         for (int tl = 0; tl < 4; ++tl) { f32x4 a = {0.f, 0.f, 0.f, 0.f};
; #pragma unroll
;             for (int kk = 0; kk < 4; ++kk) a = __builtin_amdgcn_mfma_f32_16x16x32_bf16(ka[gi & 1][tl][kk], qf[kk], a, 0, 0, 0);
;             S[gi * 4 + tl] = a; }
;         __builtin_amdgcn_sched_barrier(0);
;         if (gi + 2 < 4) { ATT_LOADK(gi & 1, gi + 2); __builtin_amdgcn_sched_barrier(0); }
;     }
.LBB0_4765:
	s_or_b64 exec, exec, s[4:5]
	s_waitcnt vmcnt(0) lgkmcnt(0)
	s_lshl_b32 s4, s7, 21
	s_or_b32 s7, s4, 0x800000
	s_add_u32 s4, s25, s7
	s_addc_u32 s5, s26, 0
	s_add_u32 s16, s18, s7
	s_addc_u32 s17, s19, 0
	v_and_b32_e32 v250, 7, v167
	v_lshl_add_u32 v250, v250, 2, s24
	v_lshrrev_b32_e32 v251, 4, v167
	v_bfe_u32 v252, v167, 3, 1
	v_lshlrev_b32_e32 v251, 4, v251
	v_lshl_or_b32 v251, v252, 6, v251
	ds_read2_b32 v[242:243], v250 offset0:0 offset1:8
	ds_read2_b32 v[244:245], v250 offset0:16 offset1:24
	ds_read2_b32 v[246:247], v250 offset0:32 offset1:40
	ds_read2_b32 v[248:249], v250 offset0:48 offset1:56
	s_waitcnt lgkmcnt(0)
	v_add_u32_e32 v252, v242, v251
	v_add_u32_e32 v253, v243, v251
	global_load_dwordx4 v[20:23], v252, s[4:5]
	global_load_dwordx4 v[24:27], v252, s[4:5] offset:128
	global_load_dwordx4 v[28:31], v253, s[4:5]
	global_load_dwordx4 v[32:35], v253, s[4:5] offset:128
	v_add_u32_e32 v252, v244, v251
	v_add_u32_e32 v253, v245, v251
	global_load_dwordx4 v[36:39], v252, s[4:5]
	global_load_dwordx4 v[40:43], v252, s[4:5] offset:128
	global_load_dwordx4 v[44:47], v253, s[4:5]
	global_load_dwordx4 v[48:51], v253, s[4:5] offset:128
	v_add_u32_e32 v252, v246, v251
	v_add_u32_e32 v253, v247, v251
	global_load_dwordx4 v[52:55], v252, s[4:5]
	global_load_dwordx4 v[56:59], v252, s[4:5] offset:128
	global_load_dwordx4 v[60:63], v253, s[4:5]
	global_load_dwordx4 v[64:67], v253, s[4:5] offset:128
	v_add_u32_e32 v252, v248, v251
	v_add_u32_e32 v253, v249, v251
	global_load_dwordx4 v[68:71], v252, s[4:5]
	global_load_dwordx4 v[72:75], v252, s[4:5] offset:128
	global_load_dwordx4 v[76:79], v253, s[4:5]
	global_load_dwordx4 v[80:83], v253, s[4:5] offset:128
	ds_read2_b32 v[242:243], v250 offset0:64 offset1:72
	ds_read2_b32 v[244:245], v250 offset0:80 offset1:88
	ds_read2_b32 v[246:247], v250 offset0:96 offset1:104
	ds_read2_b32 v[248:249], v250 offset0:112 offset1:120
	s_waitcnt lgkmcnt(0)
	v_add_u32_e32 v252, v242, v251
	v_add_u32_e32 v253, v243, v251
	global_load_dwordx4 v[170:173], v252, s[4:5]
	global_load_dwordx4 v[174:177], v252, s[4:5] offset:128
	global_load_dwordx4 v[178:181], v253, s[4:5]
	global_load_dwordx4 v[182:185], v253, s[4:5] offset:128
	v_add_u32_e32 v252, v244, v251
	v_add_u32_e32 v253, v245, v251
	global_load_dwordx4 v[186:189], v252, s[4:5]
	global_load_dwordx4 v[190:193], v252, s[4:5] offset:128
	global_load_dwordx4 v[194:197], v253, s[4:5]
	global_load_dwordx4 v[198:201], v253, s[4:5] offset:128
	v_add_u32_e32 v252, v246, v251
	v_add_u32_e32 v253, v247, v251
	global_load_dwordx4 v[202:205], v252, s[4:5]
	global_load_dwordx4 v[206:209], v252, s[4:5] offset:128
	global_load_dwordx4 v[210:213], v253, s[4:5]
	global_load_dwordx4 v[214:217], v253, s[4:5] offset:128
	v_add_u32_e32 v252, v248, v251
	v_add_u32_e32 v253, v249, v251
	global_load_dwordx4 v[218:221], v252, s[4:5]
	global_load_dwordx4 v[222:225], v252, s[4:5] offset:128
	global_load_dwordx4 v[226:229], v253, s[4:5]
	global_load_dwordx4 v[230:233], v253, s[4:5] offset:128
	s_waitcnt vmcnt(28)
	v_mfma_f32_16x16x32_bf16 v[148:151], v[20:23], v[0:3], 0
	v_mfma_f32_16x16x32_bf16 v[148:151], v[24:27], v[4:7], v[148:151]
	v_mfma_f32_16x16x32_bf16 v[234:237], v[28:31], v[0:3], 0
	v_mfma_f32_16x16x32_bf16 v[234:237], v[32:35], v[4:7], v[234:237]
	s_waitcnt vmcnt(24)
	v_mfma_f32_16x16x32_bf16 v[136:139], v[36:39], v[0:3], 0
	v_mfma_f32_16x16x32_bf16 v[136:139], v[40:43], v[4:7], v[136:139]
	v_mfma_f32_16x16x32_bf16 v[238:241], v[44:47], v[0:3], 0
	v_mfma_f32_16x16x32_bf16 v[238:241], v[48:51], v[4:7], v[238:241]
	s_nop 3
	v_permlane32_swap_b32_e32 v148, v234
	v_permlane32_swap_b32_e32 v149, v235
	v_permlane32_swap_b32_e32 v150, v236
	v_permlane32_swap_b32_e32 v151, v237
	v_add_f32_dpp v148, v234, v148 row_ror:8 row_mask:0xf bank_mask:0xf
	v_add_f32_dpp v149, v235, v149 row_ror:8 row_mask:0xf bank_mask:0xf
	v_add_f32_dpp v150, v236, v150 row_ror:8 row_mask:0xf bank_mask:0xf
	v_add_f32_dpp v151, v237, v151 row_ror:8 row_mask:0xf bank_mask:0xf
	s_waitcnt vmcnt(20)
	v_mfma_f32_16x16x32_bf16 v[124:127], v[52:55], v[0:3], 0
	v_mfma_f32_16x16x32_bf16 v[124:127], v[56:59], v[4:7], v[124:127]
	v_mfma_f32_16x16x32_bf16 v[234:237], v[60:63], v[0:3], 0
	v_mfma_f32_16x16x32_bf16 v[234:237], v[64:67], v[4:7], v[234:237]
	s_nop 3
	v_permlane32_swap_b32_e32 v136, v238
	v_permlane32_swap_b32_e32 v137, v239
	v_permlane32_swap_b32_e32 v138, v240
	v_permlane32_swap_b32_e32 v139, v241
	v_add_f32_dpp v136, v238, v136 row_ror:8 row_mask:0xf bank_mask:0xf
	v_add_f32_dpp v137, v239, v137 row_ror:8 row_mask:0xf bank_mask:0xf
	v_add_f32_dpp v138, v240, v138 row_ror:8 row_mask:0xf bank_mask:0xf
	v_add_f32_dpp v139, v241, v139 row_ror:8 row_mask:0xf bank_mask:0xf
	s_waitcnt vmcnt(16)
	v_mfma_f32_16x16x32_bf16 v[112:115], v[68:71], v[0:3], 0
	v_mfma_f32_16x16x32_bf16 v[112:115], v[72:75], v[4:7], v[112:115]
	v_mfma_f32_16x16x32_bf16 v[238:241], v[76:79], v[0:3], 0
	v_mfma_f32_16x16x32_bf16 v[238:241], v[80:83], v[4:7], v[238:241]
	s_nop 3
	v_permlane32_swap_b32_e32 v124, v234
	v_permlane32_swap_b32_e32 v125, v235
	v_permlane32_swap_b32_e32 v126, v236
	v_permlane32_swap_b32_e32 v127, v237
	v_add_f32_dpp v124, v234, v124 row_ror:8 row_mask:0xf bank_mask:0xf
	v_add_f32_dpp v125, v235, v125 row_ror:8 row_mask:0xf bank_mask:0xf
	v_add_f32_dpp v126, v236, v126 row_ror:8 row_mask:0xf bank_mask:0xf
	v_add_f32_dpp v127, v237, v127 row_ror:8 row_mask:0xf bank_mask:0xf
	s_nop 7
	v_permlane32_swap_b32_e32 v112, v238
	v_permlane32_swap_b32_e32 v113, v239
	v_permlane32_swap_b32_e32 v114, v240
	v_permlane32_swap_b32_e32 v115, v241
	v_add_f32_dpp v112, v238, v112 row_ror:8 row_mask:0xf bank_mask:0xf
	v_add_f32_dpp v113, v239, v113 row_ror:8 row_mask:0xf bank_mask:0xf
	v_add_f32_dpp v114, v240, v114 row_ror:8 row_mask:0xf bank_mask:0xf
	v_add_f32_dpp v115, v241, v115 row_ror:8 row_mask:0xf bank_mask:0xf
	ds_read2_b32 v[242:243], v250 offset0:128 offset1:136
	ds_read2_b32 v[244:245], v250 offset0:144 offset1:152
	ds_read2_b32 v[246:247], v250 offset0:160 offset1:168
	ds_read2_b32 v[248:249], v250 offset0:176 offset1:184
	s_waitcnt lgkmcnt(0)
; #define ATT_LOADK(buf, grp) do { _Pragma("unroll") for (int tl = 0; tl < 4; ++tl) { const unsigned ko = li[((grp) * 4 + tl) * 16 + n] + (unsigned)g * 16u; \
;         _Pragma("unroll") for (int kk = 0; kk < 4; ++kk) ka[buf][tl][kk] = *(const bf16x8*)((const char*)Kb + (ko + kk * 64u)); } } while (0)
; __device__ __forceinline__ void attend_one(unsigned char* ws, LAS unsigned char* lds, int wave, int bb, int t, int kvh, int lane) {
;     ...
;     ATT_LOADK(0, 0); ATT_LOADK(1, 1);
;     __builtin_amdgcn_sched_barrier(0);
;     f32x4 S[16];
; #pragma unroll
;     for (int gi = 0; gi < 4; ++gi) {
; #pragma unroll
;         for (int tl = 0; tl < 4; ++tl) { f32x4 a = {0.f, 0.f, 0.f, 0.f};
; #pragma unroll
;             for (int kk = 0; kk < 4; ++kk) a = __builtin_amdgcn_mfma_f32_16x16x32_bf16(ka[gi & 1][tl][kk], qf[kk], a, 0, 0, 0);
;             S[gi * 4 + tl] = a; }
;         __builtin_amdgcn_sched_barrier(0);
;         if (gi + 2 < 4) { ATT_LOADK(gi & 1, gi + 2); __builtin_amdgcn_sched_barrier(0); }
;     }
	v_add_u32_e32 v252, v242, v251
	v_add_u32_e32 v253, v243, v251
	global_load_dwordx4 v[20:23], v252, s[4:5]
	global_load_dwordx4 v[24:27], v252, s[4:5] offset:128
	global_load_dwordx4 v[28:31], v253, s[4:5]
	global_load_dwordx4 v[32:35], v253, s[4:5] offset:128
	v_add_u32_e32 v252, v244, v251
	v_add_u32_e32 v253, v245, v251
	global_load_dwordx4 v[36:39], v252, s[4:5]
	global_load_dwordx4 v[40:43], v252, s[4:5] offset:128
	global_load_dwordx4 v[44:47], v253, s[4:5]
	global_load_dwordx4 v[48:51], v253, s[4:5] offset:128
	v_add_u32_e32 v252, v246, v251
	v_add_u32_e32 v253, v247, v251
	global_load_dwordx4 v[52:55], v252, s[4:5]
	global_load_dwordx4 v[56:59], v252, s[4:5] offset:128
	global_load_dwordx4 v[60:63], v253, s[4:5]
	global_load_dwordx4 v[64:67], v253, s[4:5] offset:128
	v_add_u32_e32 v252, v248, v251
	v_add_u32_e32 v253, v249, v251
	global_load_dwordx4 v[68:71], v252, s[4:5]
	global_load_dwordx4 v[72:75], v252, s[4:5] offset:128
	global_load_dwordx4 v[76:79], v253, s[4:5]
	global_load_dwordx4 v[80:83], v253, s[4:5] offset:128
	s_waitcnt vmcnt(28)
	v_mfma_f32_16x16x32_bf16 v[152:155], v[170:173], v[0:3], 0
	v_mfma_f32_16x16x32_bf16 v[152:155], v[174:177], v[4:7], v[152:155]
	v_mfma_f32_16x16x32_bf16 v[234:237], v[178:181], v[0:3], 0
	v_mfma_f32_16x16x32_bf16 v[234:237], v[182:185], v[4:7], v[234:237]
	s_waitcnt vmcnt(24)
	v_mfma_f32_16x16x32_bf16 v[140:143], v[186:189], v[0:3], 0
	v_mfma_f32_16x16x32_bf16 v[140:143], v[190:193], v[4:7], v[140:143]
	v_mfma_f32_16x16x32_bf16 v[238:241], v[194:197], v[0:3], 0
	v_mfma_f32_16x16x32_bf16 v[238:241], v[198:201], v[4:7], v[238:241]
	s_nop 3
	v_permlane32_swap_b32_e32 v152, v234
	v_permlane32_swap_b32_e32 v153, v235
	v_permlane32_swap_b32_e32 v154, v236
	v_permlane32_swap_b32_e32 v155, v237
	v_add_f32_dpp v152, v234, v152 row_ror:8 row_mask:0xf bank_mask:0xf
	v_add_f32_dpp v153, v235, v153 row_ror:8 row_mask:0xf bank_mask:0xf
	v_add_f32_dpp v154, v236, v154 row_ror:8 row_mask:0xf bank_mask:0xf
	v_add_f32_dpp v155, v237, v155 row_ror:8 row_mask:0xf bank_mask:0xf
	s_waitcnt vmcnt(20)
	v_mfma_f32_16x16x32_bf16 v[128:131], v[202:205], v[0:3], 0
	v_mfma_f32_16x16x32_bf16 v[128:131], v[206:209], v[4:7], v[128:131]
	v_mfma_f32_16x16x32_bf16 v[234:237], v[210:213], v[0:3], 0
	v_mfma_f32_16x16x32_bf16 v[234:237], v[214:217], v[4:7], v[234:237]
	s_nop 3
	v_permlane32_swap_b32_e32 v140, v238
	v_permlane32_swap_b32_e32 v141, v239
	v_permlane32_swap_b32_e32 v142, v240
	v_permlane32_swap_b32_e32 v143, v241
	v_add_f32_dpp v140, v238, v140 row_ror:8 row_mask:0xf bank_mask:0xf
	v_add_f32_dpp v141, v239, v141 row_ror:8 row_mask:0xf bank_mask:0xf
	v_add_f32_dpp v142, v240, v142 row_ror:8 row_mask:0xf bank_mask:0xf
	v_add_f32_dpp v143, v241, v143 row_ror:8 row_mask:0xf bank_mask:0xf
	s_waitcnt vmcnt(16)
	v_mfma_f32_16x16x32_bf16 v[116:119], v[218:221], v[0:3], 0
	v_mfma_f32_16x16x32_bf16 v[116:119], v[222:225], v[4:7], v[116:119]
	v_mfma_f32_16x16x32_bf16 v[238:241], v[226:229], v[0:3], 0
	v_mfma_f32_16x16x32_bf16 v[238:241], v[230:233], v[4:7], v[238:241]
	s_nop 3
	v_permlane32_swap_b32_e32 v128, v234
	v_permlane32_swap_b32_e32 v129, v235
	v_permlane32_swap_b32_e32 v130, v236
	v_permlane32_swap_b32_e32 v131, v237
	v_add_f32_dpp v128, v234, v128 row_ror:8 row_mask:0xf bank_mask:0xf
	v_add_f32_dpp v129, v235, v129 row_ror:8 row_mask:0xf bank_mask:0xf
	v_add_f32_dpp v130, v236, v130 row_ror:8 row_mask:0xf bank_mask:0xf
	v_add_f32_dpp v131, v237, v131 row_ror:8 row_mask:0xf bank_mask:0xf
	s_nop 7
	v_permlane32_swap_b32_e32 v116, v238
	v_permlane32_swap_b32_e32 v117, v239
	v_permlane32_swap_b32_e32 v118, v240
	v_permlane32_swap_b32_e32 v119, v241
	v_add_f32_dpp v116, v238, v116 row_ror:8 row_mask:0xf bank_mask:0xf
	v_add_f32_dpp v117, v239, v117 row_ror:8 row_mask:0xf bank_mask:0xf
	v_add_f32_dpp v118, v240, v118 row_ror:8 row_mask:0xf bank_mask:0xf
	v_add_f32_dpp v119, v241, v119 row_ror:8 row_mask:0xf bank_mask:0xf
	ds_read2_b32 v[242:243], v250 offset0:192 offset1:200
	ds_read2_b32 v[244:245], v250 offset0:208 offset1:216
	ds_read2_b32 v[246:247], v250 offset0:224 offset1:232
	ds_read2_b32 v[248:249], v250 offset0:240 offset1:248
	s_waitcnt lgkmcnt(0)
	v_add_u32_e32 v252, v242, v251
	v_add_u32_e32 v253, v243, v251
	global_load_dwordx4 v[170:173], v252, s[4:5]
	global_load_dwordx4 v[174:177], v252, s[4:5] offset:128
	global_load_dwordx4 v[178:181], v253, s[4:5]
	global_load_dwordx4 v[182:185], v253, s[4:5] offset:128
	v_add_u32_e32 v252, v244, v251
	v_add_u32_e32 v253, v245, v251
	global_load_dwordx4 v[186:189], v252, s[4:5]
	global_load_dwordx4 v[190:193], v252, s[4:5] offset:128
	global_load_dwordx4 v[194:197], v253, s[4:5]
	global_load_dwordx4 v[198:201], v253, s[4:5] offset:128
	v_add_u32_e32 v252, v246, v251
	v_add_u32_e32 v253, v247, v251
	global_load_dwordx4 v[202:205], v252, s[4:5]
	global_load_dwordx4 v[206:209], v252, s[4:5] offset:128
	global_load_dwordx4 v[210:213], v253, s[4:5]
	global_load_dwordx4 v[214:217], v253, s[4:5] offset:128
	v_add_u32_e32 v252, v248, v251
	v_add_u32_e32 v253, v249, v251
	global_load_dwordx4 v[218:221], v252, s[4:5]
	global_load_dwordx4 v[222:225], v252, s[4:5] offset:128
	global_load_dwordx4 v[226:229], v253, s[4:5]
	global_load_dwordx4 v[230:233], v253, s[4:5] offset:128
	s_waitcnt vmcnt(28)
	v_mfma_f32_16x16x32_bf16 v[156:159], v[20:23], v[0:3], 0
	v_mfma_f32_16x16x32_bf16 v[156:159], v[24:27], v[4:7], v[156:159]
	v_mfma_f32_16x16x32_bf16 v[234:237], v[28:31], v[0:3], 0
	v_mfma_f32_16x16x32_bf16 v[234:237], v[32:35], v[4:7], v[234:237]
	s_waitcnt vmcnt(24)
; #define ATT_LOADK(buf, grp) do { _Pragma("unroll") for (int tl = 0; tl < 4; ++tl) { const unsigned ko = li[((grp) * 4 + tl) * 16 + n] + (unsigned)g * 16u; \
;         _Pragma("unroll") for (int kk = 0; kk < 4; ++kk) ka[buf][tl][kk] = *(const bf16x8*)((const char*)Kb + (ko + kk * 64u)); } } while (0)
; #define ATT_LOADV(buf, ks) do { const u32x4 i0 = *(const LAS u32x4*)(li + (ks) * 32 + 4 * g), i1 = *(const LAS u32x4*)(li + (ks) * 32 + 16 + 4 * g); \
;         const unsigned kidx[8] = {i0.x, i0.y, i0.z, i0.w, i1.x, i1.y, i1.z, i1.w}; \
;         _Pragma("unroll") for (int jj = 0; jj < 8; ++jj) R[buf][jj] = *(const u32x4*)((const char*)Vb + (kidx[jj] + (unsigned)n * 16u)); } while (0)
; __device__ __forceinline__ void attend_one(unsigned char* ws, LAS unsigned char* lds, int wave, int bb, int t, int kvh, int lane) {
;     ...
; #pragma unroll
;     for (int gi = 0; gi < 4; ++gi) {
; #pragma unroll
;         for (int tl = 0; tl < 4; ++tl) { f32x4 a = {0.f, 0.f, 0.f, 0.f};
; #pragma unroll
;             for (int kk = 0; kk < 4; ++kk) a = __builtin_amdgcn_mfma_f32_16x16x32_bf16(ka[gi & 1][tl][kk], qf[kk], a, 0, 0, 0);
;             S[gi * 4 + tl] = a; }
;         __builtin_amdgcn_sched_barrier(0);
;         if (gi + 2 < 4) { ATT_LOADK(gi & 1, gi + 2); __builtin_amdgcn_sched_barrier(0); }
;     }
;     ...
;     u32x4 R[3][8];
;     ...
;     ATT_LOADV(0, 0); ATT_LOADV(1, 1); ATT_LOADV(2, 2);
	v_mfma_f32_16x16x32_bf16 v[144:147], v[36:39], v[0:3], 0
	v_mfma_f32_16x16x32_bf16 v[144:147], v[40:43], v[4:7], v[144:147]
	v_mfma_f32_16x16x32_bf16 v[238:241], v[44:47], v[0:3], 0
	v_mfma_f32_16x16x32_bf16 v[238:241], v[48:51], v[4:7], v[238:241]
	s_nop 3
	v_permlane32_swap_b32_e32 v156, v234
	v_permlane32_swap_b32_e32 v157, v235
	v_permlane32_swap_b32_e32 v158, v236
	v_permlane32_swap_b32_e32 v159, v237
	v_add_f32_dpp v156, v234, v156 row_ror:8 row_mask:0xf bank_mask:0xf
	v_add_f32_dpp v157, v235, v157 row_ror:8 row_mask:0xf bank_mask:0xf
	v_add_f32_dpp v158, v236, v158 row_ror:8 row_mask:0xf bank_mask:0xf
	v_add_f32_dpp v159, v237, v159 row_ror:8 row_mask:0xf bank_mask:0xf
	s_waitcnt vmcnt(20)
	v_mfma_f32_16x16x32_bf16 v[132:135], v[52:55], v[0:3], 0
	v_mfma_f32_16x16x32_bf16 v[132:135], v[56:59], v[4:7], v[132:135]
	v_mfma_f32_16x16x32_bf16 v[234:237], v[60:63], v[0:3], 0
	v_mfma_f32_16x16x32_bf16 v[234:237], v[64:67], v[4:7], v[234:237]
	s_nop 3
	v_permlane32_swap_b32_e32 v144, v238
	v_permlane32_swap_b32_e32 v145, v239
	v_permlane32_swap_b32_e32 v146, v240
	v_permlane32_swap_b32_e32 v147, v241
	v_add_f32_dpp v144, v238, v144 row_ror:8 row_mask:0xf bank_mask:0xf
	v_add_f32_dpp v145, v239, v145 row_ror:8 row_mask:0xf bank_mask:0xf
	v_add_f32_dpp v146, v240, v146 row_ror:8 row_mask:0xf bank_mask:0xf
	v_add_f32_dpp v147, v241, v147 row_ror:8 row_mask:0xf bank_mask:0xf
	s_waitcnt vmcnt(16)
	v_mfma_f32_16x16x32_bf16 v[120:123], v[68:71], v[0:3], 0
	v_mfma_f32_16x16x32_bf16 v[120:123], v[72:75], v[4:7], v[120:123]
	v_mfma_f32_16x16x32_bf16 v[238:241], v[76:79], v[0:3], 0
	v_mfma_f32_16x16x32_bf16 v[238:241], v[80:83], v[4:7], v[238:241]
	s_nop 3
	v_permlane32_swap_b32_e32 v132, v234
	v_permlane32_swap_b32_e32 v133, v235
	v_permlane32_swap_b32_e32 v134, v236
	v_permlane32_swap_b32_e32 v135, v237
	v_add_f32_dpp v132, v234, v132 row_ror:8 row_mask:0xf bank_mask:0xf
	v_add_f32_dpp v133, v235, v133 row_ror:8 row_mask:0xf bank_mask:0xf
	v_add_f32_dpp v134, v236, v134 row_ror:8 row_mask:0xf bank_mask:0xf
	v_add_f32_dpp v135, v237, v135 row_ror:8 row_mask:0xf bank_mask:0xf
	s_nop 7
	v_permlane32_swap_b32_e32 v120, v238
	v_permlane32_swap_b32_e32 v121, v239
	v_permlane32_swap_b32_e32 v122, v240
	v_permlane32_swap_b32_e32 v123, v241
	v_add_f32_dpp v120, v238, v120 row_ror:8 row_mask:0xf bank_mask:0xf
	v_add_f32_dpp v121, v239, v121 row_ror:8 row_mask:0xf bank_mask:0xf
	v_add_f32_dpp v122, v240, v122 row_ror:8 row_mask:0xf bank_mask:0xf
	v_add_f32_dpp v123, v241, v123 row_ror:8 row_mask:0xf bank_mask:0xf
	s_waitcnt vmcnt(12)
	v_mfma_f32_16x16x32_bf16 v[108:111], v[170:173], v[0:3], 0
	v_mfma_f32_16x16x32_bf16 v[108:111], v[174:177], v[4:7], v[108:111]
	v_mfma_f32_16x16x32_bf16 v[234:237], v[178:181], v[0:3], 0
	v_mfma_f32_16x16x32_bf16 v[234:237], v[182:185], v[4:7], v[234:237]
	s_waitcnt vmcnt(8)
	v_mfma_f32_16x16x32_bf16 v[104:107], v[186:189], v[0:3], 0
	v_mfma_f32_16x16x32_bf16 v[104:107], v[190:193], v[4:7], v[104:107]
	v_mfma_f32_16x16x32_bf16 v[238:241], v[194:197], v[0:3], 0
	v_mfma_f32_16x16x32_bf16 v[238:241], v[198:201], v[4:7], v[238:241]
	s_nop 3
	v_permlane32_swap_b32_e32 v108, v234
	v_permlane32_swap_b32_e32 v109, v235
	v_permlane32_swap_b32_e32 v110, v236
	v_permlane32_swap_b32_e32 v111, v237
	v_add_f32_dpp v108, v234, v108 row_ror:8 row_mask:0xf bank_mask:0xf
	v_add_f32_dpp v109, v235, v109 row_ror:8 row_mask:0xf bank_mask:0xf
	v_add_f32_dpp v110, v236, v110 row_ror:8 row_mask:0xf bank_mask:0xf
	v_add_f32_dpp v111, v237, v111 row_ror:8 row_mask:0xf bank_mask:0xf
	s_waitcnt vmcnt(4)
	v_mfma_f32_16x16x32_bf16 v[100:103], v[202:205], v[0:3], 0
	v_mfma_f32_16x16x32_bf16 v[100:103], v[206:209], v[4:7], v[100:103]
	v_mfma_f32_16x16x32_bf16 v[234:237], v[210:213], v[0:3], 0
	v_mfma_f32_16x16x32_bf16 v[234:237], v[214:217], v[4:7], v[234:237]
	s_nop 3
	v_permlane32_swap_b32_e32 v104, v238
	v_permlane32_swap_b32_e32 v105, v239
	v_permlane32_swap_b32_e32 v106, v240
	v_permlane32_swap_b32_e32 v107, v241
	v_add_f32_dpp v104, v238, v104 row_ror:8 row_mask:0xf bank_mask:0xf
	v_add_f32_dpp v105, v239, v105 row_ror:8 row_mask:0xf bank_mask:0xf
	v_add_f32_dpp v106, v240, v106 row_ror:8 row_mask:0xf bank_mask:0xf
	v_add_f32_dpp v107, v241, v107 row_ror:8 row_mask:0xf bank_mask:0xf
	s_waitcnt vmcnt(0)
	v_mfma_f32_16x16x32_bf16 v[96:99], v[218:221], v[0:3], 0
	v_mfma_f32_16x16x32_bf16 v[96:99], v[222:225], v[4:7], v[96:99]
	v_mfma_f32_16x16x32_bf16 v[238:241], v[226:229], v[0:3], 0
	v_mfma_f32_16x16x32_bf16 v[238:241], v[230:233], v[4:7], v[238:241]
	s_nop 3
	v_permlane32_swap_b32_e32 v100, v234
	v_permlane32_swap_b32_e32 v101, v235
	v_permlane32_swap_b32_e32 v102, v236
	v_permlane32_swap_b32_e32 v103, v237
	v_add_f32_dpp v100, v234, v100 row_ror:8 row_mask:0xf bank_mask:0xf
	v_add_f32_dpp v101, v235, v101 row_ror:8 row_mask:0xf bank_mask:0xf
	v_add_f32_dpp v102, v236, v102 row_ror:8 row_mask:0xf bank_mask:0xf
	v_add_f32_dpp v103, v237, v103 row_ror:8 row_mask:0xf bank_mask:0xf
	s_nop 7
	v_permlane32_swap_b32_e32 v96, v238
	v_permlane32_swap_b32_e32 v97, v239
	v_permlane32_swap_b32_e32 v98, v240
	v_permlane32_swap_b32_e32 v99, v241
	v_add_f32_dpp v96, v238, v96 row_ror:8 row_mask:0xf bank_mask:0xf
	v_add_f32_dpp v97, v239, v97 row_ror:8 row_mask:0xf bank_mask:0xf
	v_add_f32_dpp v98, v240, v98 row_ror:8 row_mask:0xf bank_mask:0xf
	v_add_f32_dpp v99, v241, v99 row_ror:8 row_mask:0xf bank_mask:0xf
	v_lshl_add_u32 v163, v168, 4, s24
	s_nop 3
	ds_read_b128 v[0:3], v163
	ds_read_b128 v[4:7], v163 offset:64
	v_lshlrev_b32_e32 v160, 4, v18
	s_waitcnt lgkmcnt(1)
; #define ATT_LOADV(buf, ks) do { const u32x4 i0 = *(const LAS u32x4*)(li + (ks) * 32 + 4 * g), i1 = *(const LAS u32x4*)(li + (ks) * 32 + 16 + 4 * g); \
;         const unsigned kidx[8] = {i0.x, i0.y, i0.z, i0.w, i1.x, i1.y, i1.z, i1.w}; \
;         _Pragma("unroll") for (int jj = 0; jj < 8; ++jj) R[buf][jj] = *(const u32x4*)((const char*)Vb + (kidx[jj] + (unsigned)n * 16u)); } while (0)
; __device__ __forceinline__ void attend_one(unsigned char* ws, LAS unsigned char* lds, int wave, int bb, int t, int kvh, int lane) {
;     ...
;     ATT_LOADV(0, 0); ATT_LOADV(1, 1); ATT_LOADV(2, 2);
	v_add_u32_e32 v0, v0, v160
	v_add_u32_e32 v1, v1, v160
	global_load_dwordx4 v[80:83], v0, s[16:17]
	global_load_dwordx4 v[84:87], v1, s[16:17]
	v_add_u32_e32 v0, v2, v160
	v_add_u32_e32 v1, v3, v160
	global_load_dwordx4 v[64:67], v0, s[16:17]
	global_load_dwordx4 v[68:71], v1, s[16:17]
	s_waitcnt lgkmcnt(0)
	v_add_u32_e32 v0, v4, v160
	v_add_u32_e32 v1, v5, v160
	global_load_dwordx4 v[72:75], v0, s[16:17]
	global_load_dwordx4 v[76:79], v1, s[16:17]
	ds_read_b128 v[0:3], v163 offset:128
	v_add_u32_e32 v4, v6, v160
	v_add_u32_e32 v5, v7, v160
	global_load_dwordx4 v[88:91], v4, s[16:17]
	global_load_dwordx4 v[92:95], v5, s[16:17]
	ds_read_b128 v[4:7], v163 offset:192
	s_waitcnt lgkmcnt(1)
	v_add_u32_e32 v0, v0, v160
	v_add_u32_e32 v1, v1, v160
	global_load_dwordx4 v[48:51], v0, s[16:17]
	global_load_dwordx4 v[52:55], v1, s[16:17]
	v_add_u32_e32 v0, v2, v160
	v_add_u32_e32 v1, v3, v160
	global_load_dwordx4 v[32:35], v0, s[16:17]
	global_load_dwordx4 v[36:39], v1, s[16:17]
	s_waitcnt lgkmcnt(0)
	v_add_u32_e32 v0, v4, v160
	v_add_u32_e32 v1, v5, v160
	global_load_dwordx4 v[40:43], v0, s[16:17]
	global_load_dwordx4 v[44:47], v1, s[16:17]
	v_add_u32_e32 v4, v6, v160
	ds_read_b128 v[0:3], v163 offset:256
	v_add_u32_e32 v5, v7, v160
	global_load_dwordx4 v[56:59], v4, s[16:17]
	global_load_dwordx4 v[60:63], v5, s[16:17]
	ds_read_b128 v[14:17], v163 offset:320
	s_waitcnt lgkmcnt(1)
	v_add_u32_e32 v0, v0, v160
	v_add_u32_e32 v1, v1, v160
	global_load_dwordx4 v[24:27], v0, s[16:17]
	global_load_dwordx4 v[28:31], v1, s[16:17]
	v_add_u32_e32 v0, v2, v160
	v_add_u32_e32 v4, v3, v160
	s_waitcnt lgkmcnt(0)
	v_add_u32_e32 v8, v14, v160
	v_add_u32_e32 v12, v15, v160
	v_add_u32_e32 v16, v16, v160
	v_add_u32_e32 v20, v17, v160
	global_load_dwordx4 v[0:3], v0, s[16:17]
	s_nop 0
	global_load_dwordx4 v[4:7], v4, s[16:17]
	s_nop 0
	global_load_dwordx4 v[8:11], v8, s[16:17]
	s_nop 0
	global_load_dwordx4 v[12:15], v12, s[16:17]
	s_nop 0
	global_load_dwordx4 v[16:19], v16, s[16:17]
	s_nop 0
	global_load_dwordx4 v[20:23], v20, s[16:17]
	s_cmpk_gt_i32 s6, 0xfe
	s_cbranch_scc1 .LBB0_4767
; __device__ __forceinline__ void attend_one(unsigned char* ws, LAS unsigned char* lds, int wave, int bb, int t, int kvh, int lane) {
;     ...
;     if (cnt < 256) {
; #pragma unroll
;         for (int kt = 0; kt < 16; ++kt)
; #pragma unroll
;             for (int j = 0; j < 4; ++j) if (4 * g + j >= cnt - kt * 16) S[kt][j] = -3.0e38f;
;     }
	v_lshlrev_b32_e32 v169, 2, v168
	s_min_i32 s31, s6, 0xff
	v_mov_b32_e32 v168, s28
	v_cmp_lt_i32_e32 vcc, s31, v169
	v_or_b32_e32 v171, 3, v169
	v_or_b32_e32 v170, 1, v169
	v_cndmask_b32_e32 v168, v148, v168, vcc
	v_cmp_gt_i32_e32 vcc, s31, v169
	s_add_i32 s8, s31, -15
	v_cmp_gt_i32_e64 s[4:5], s8, v170
	v_cndmask_b32_e32 v148, v168, v148, vcc
	v_or_b32_e32 v168, 2, v169
	v_cndmask_b32_e32 v149, v166, v149, vcc
	v_cmp_ge_i32_e32 vcc, s31, v168
	v_cmp_gt_i32_e64 s[6:7], s8, v168
	s_nop 0
	v_cndmask_b32_e32 v150, v166, v150, vcc
	v_cmp_ge_i32_e32 vcc, s31, v171
	s_nop 1
	v_cndmask_b32_e32 v151, v166, v151, vcc
	v_cmp_gt_i32_e32 vcc, s8, v169
	v_cmp_gt_i32_e64 s[8:9], s8, v171
	s_or_b64 s[6:7], s[8:9], s[6:7]
	s_or_b64 s[4:5], s[6:7], s[4:5]
	v_cndmask_b32_e64 v139, v166, v139, s[8:9]
	s_or_b64 vcc, s[4:5], vcc
	s_sub_i32 s8, s31, 31
	v_cndmask_b32_e64 v138, v166, v138, s[6:7]
	v_cndmask_b32_e64 v137, v166, v137, s[4:5]
	v_cndmask_b32_e32 v136, v166, v136, vcc
	v_cmp_gt_i32_e32 vcc, s8, v169
	v_cmp_gt_i32_e64 s[4:5], s8, v170
	v_cmp_gt_i32_e64 s[6:7], s8, v168
	v_cmp_gt_i32_e64 s[8:9], s8, v171
	s_or_b64 s[6:7], s[8:9], s[6:7]
	s_or_b64 s[4:5], s[6:7], s[4:5]
	v_cndmask_b32_e64 v127, v166, v127, s[8:9]
	s_or_b64 vcc, s[4:5], vcc
	s_sub_i32 s8, s31, 47
	v_cndmask_b32_e64 v126, v166, v126, s[6:7]
	v_cndmask_b32_e64 v125, v166, v125, s[4:5]
	v_cndmask_b32_e32 v124, v166, v124, vcc
	v_cmp_gt_i32_e32 vcc, s8, v169
	v_cmp_gt_i32_e64 s[4:5], s8, v170
	v_cmp_gt_i32_e64 s[6:7], s8, v168
	v_cmp_gt_i32_e64 s[8:9], s8, v171
	s_or_b64 s[6:7], s[8:9], s[6:7]
	s_or_b64 s[4:5], s[6:7], s[4:5]
	v_cndmask_b32_e64 v115, v166, v115, s[8:9]
	s_or_b64 vcc, s[4:5], vcc
	s_sub_i32 s8, s31, 63
	v_cndmask_b32_e64 v114, v166, v114, s[6:7]
	v_cndmask_b32_e64 v113, v166, v113, s[4:5]
	v_cndmask_b32_e32 v112, v166, v112, vcc
	v_cmp_gt_i32_e32 vcc, s8, v169
	v_cmp_gt_i32_e64 s[4:5], s8, v170
	v_cmp_gt_i32_e64 s[6:7], s8, v168
	v_cmp_gt_i32_e64 s[8:9], s8, v171
	s_or_b64 s[6:7], s[8:9], s[6:7]
	s_or_b64 s[4:5], s[6:7], s[4:5]
	v_cndmask_b32_e64 v155, v166, v155, s[8:9]
	s_or_b64 vcc, s[4:5], vcc
	s_add_i32 s8, s31, 0xffffffb1
	v_cndmask_b32_e64 v154, v166, v154, s[6:7]
	v_cndmask_b32_e64 v153, v166, v153, s[4:5]
	v_cndmask_b32_e32 v152, v166, v152, vcc
	v_cmp_gt_i32_e32 vcc, s8, v169
	v_cmp_gt_i32_e64 s[4:5], s8, v170
	v_cmp_gt_i32_e64 s[6:7], s8, v168
	v_cmp_gt_i32_e64 s[8:9], s8, v171
	s_or_b64 s[6:7], s[8:9], s[6:7]
	s_or_b64 s[4:5], s[6:7], s[4:5]
	v_cndmask_b32_e64 v143, v166, v143, s[8:9]
	s_or_b64 vcc, s[4:5], vcc
	s_add_i32 s8, s31, 0xffffffa1
	v_cndmask_b32_e64 v142, v166, v142, s[6:7]
	v_cndmask_b32_e64 v141, v166, v141, s[4:5]
	v_cndmask_b32_e32 v140, v166, v140, vcc
	v_cmp_gt_i32_e32 vcc, s8, v169
	v_cmp_gt_i32_e64 s[4:5], s8, v170
	v_cmp_gt_i32_e64 s[6:7], s8, v168
	v_cmp_gt_i32_e64 s[8:9], s8, v171
	s_or_b64 s[6:7], s[8:9], s[6:7]
	s_or_b64 s[4:5], s[6:7], s[4:5]
	v_cndmask_b32_e64 v131, v166, v131, s[8:9]
	s_or_b64 vcc, s[4:5], vcc
	s_add_i32 s8, s31, 0xffffff91
	v_cndmask_b32_e64 v130, v166, v130, s[6:7]
	v_cndmask_b32_e64 v129, v166, v129, s[4:5]
	v_cndmask_b32_e32 v128, v166, v128, vcc
	v_cmp_gt_i32_e32 vcc, s8, v169
	v_cmp_gt_i32_e64 s[4:5], s8, v170
	v_cmp_gt_i32_e64 s[6:7], s8, v168
	v_cmp_gt_i32_e64 s[8:9], s8, v171
	s_or_b64 s[6:7], s[8:9], s[6:7]
	s_or_b64 s[4:5], s[6:7], s[4:5]
	v_cndmask_b32_e64 v119, v166, v119, s[8:9]
	s_or_b64 vcc, s[4:5], vcc
	s_add_i32 s8, s31, 0xffffff81
	v_cndmask_b32_e64 v118, v166, v118, s[6:7]
	v_cndmask_b32_e64 v117, v166, v117, s[4:5]
	v_cndmask_b32_e32 v116, v166, v116, vcc
	v_cmp_gt_i32_e32 vcc, s8, v169
	v_cmp_gt_i32_e64 s[4:5], s8, v170
	v_cmp_gt_i32_e64 s[6:7], s8, v168
	v_cmp_gt_i32_e64 s[8:9], s8, v171
	s_or_b64 s[6:7], s[8:9], s[6:7]
	s_or_b64 s[4:5], s[6:7], s[4:5]
	v_cndmask_b32_e64 v159, v166, v159, s[8:9]
	s_or_b64 vcc, s[4:5], vcc
	s_add_i32 s8, s31, 0xffffff71
	v_cndmask_b32_e64 v158, v166, v158, s[6:7]
	v_cndmask_b32_e64 v157, v166, v157, s[4:5]
	v_cndmask_b32_e32 v156, v166, v156, vcc
	v_cmp_gt_i32_e32 vcc, s8, v169
	v_cmp_gt_i32_e64 s[4:5], s8, v170
	v_cmp_gt_i32_e64 s[6:7], s8, v168
	v_cmp_gt_i32_e64 s[8:9], s8, v171
	s_or_b64 s[6:7], s[8:9], s[6:7]
	s_or_b64 s[4:5], s[6:7], s[4:5]
	v_cndmask_b32_e64 v147, v166, v147, s[8:9]
	s_or_b64 vcc, s[4:5], vcc
	s_add_i32 s8, s31, 0xffffff61
	v_cndmask_b32_e64 v146, v166, v146, s[6:7]
	v_cndmask_b32_e64 v145, v166, v145, s[4:5]
	v_cndmask_b32_e32 v144, v166, v144, vcc
	v_cmp_gt_i32_e32 vcc, s8, v169
	v_cmp_gt_i32_e64 s[4:5], s8, v170
	v_cmp_gt_i32_e64 s[6:7], s8, v168
	v_cmp_gt_i32_e64 s[8:9], s8, v171
	s_or_b64 s[6:7], s[8:9], s[6:7]
	s_or_b64 s[4:5], s[6:7], s[4:5]
	v_cndmask_b32_e64 v135, v166, v135, s[8:9]
	s_or_b64 vcc, s[4:5], vcc
	s_add_i32 s8, s31, 0xffffff51
	v_cndmask_b32_e64 v134, v166, v134, s[6:7]
	v_cndmask_b32_e64 v133, v166, v133, s[4:5]
	v_cndmask_b32_e32 v132, v166, v132, vcc
	v_cmp_gt_i32_e32 vcc, s8, v169
	v_cmp_gt_i32_e64 s[4:5], s8, v170
	v_cmp_gt_i32_e64 s[6:7], s8, v168
	v_cmp_gt_i32_e64 s[8:9], s8, v171
	s_or_b64 s[6:7], s[8:9], s[6:7]
	s_or_b64 s[4:5], s[6:7], s[4:5]
	v_cndmask_b32_e64 v123, v166, v123, s[8:9]
	s_or_b64 vcc, s[4:5], vcc
	s_add_i32 s8, s31, 0xffffff41
	v_cndmask_b32_e64 v122, v166, v122, s[6:7]
	v_cndmask_b32_e64 v121, v166, v121, s[4:5]
	v_cndmask_b32_e32 v120, v166, v120, vcc
	v_cmp_gt_i32_e32 vcc, s8, v169
	v_cmp_gt_i32_e64 s[4:5], s8, v170
	v_cmp_gt_i32_e64 s[6:7], s8, v168
	v_cmp_gt_i32_e64 s[8:9], s8, v171
	s_or_b64 s[6:7], s[8:9], s[6:7]
	s_or_b64 s[4:5], s[6:7], s[4:5]
	v_cndmask_b32_e64 v111, v166, v111, s[8:9]
	s_or_b64 vcc, s[4:5], vcc
	s_add_i32 s8, s31, 0xffffff31
	v_cndmask_b32_e64 v110, v166, v110, s[6:7]
	v_cndmask_b32_e64 v109, v166, v109, s[4:5]
	v_cndmask_b32_e32 v108, v166, v108, vcc
	v_cmp_gt_i32_e32 vcc, s8, v169
	v_cmp_gt_i32_e64 s[4:5], s8, v170
	v_cmp_gt_i32_e64 s[6:7], s8, v168
	v_cmp_gt_i32_e64 s[8:9], s8, v171
	s_or_b64 s[6:7], s[8:9], s[6:7]
	s_or_b64 s[4:5], s[6:7], s[4:5]
	v_cndmask_b32_e64 v107, v166, v107, s[8:9]
	s_or_b64 vcc, s[4:5], vcc
	s_add_i32 s8, s31, 0xffffff21
	v_cndmask_b32_e64 v106, v166, v106, s[6:7]
	v_cndmask_b32_e64 v105, v166, v105, s[4:5]
	v_cndmask_b32_e32 v104, v166, v104, vcc
	v_cmp_gt_i32_e32 vcc, s8, v169
	v_cmp_gt_i32_e64 s[4:5], s8, v170
	v_cmp_gt_i32_e64 s[6:7], s8, v168
	v_cmp_gt_i32_e64 s[8:9], s8, v171
	s_or_b64 s[6:7], s[8:9], s[6:7]
	s_addk_i32 s31, 0xff11
	v_cndmask_b32_e64 v103, v166, v103, s[8:9]
	v_cndmask_b32_e64 v102, v166, v102, s[6:7]
	s_or_b64 s[4:5], s[6:7], s[4:5]
	v_cmp_gt_i32_e64 s[6:7], s31, v168
	v_cmp_gt_i32_e64 s[8:9], s31, v171
	v_cndmask_b32_e64 v101, v166, v101, s[4:5]
	s_or_b64 vcc, s[4:5], vcc
	v_cmp_gt_i32_e64 s[4:5], s31, v170
	s_or_b64 s[6:7], s[8:9], s[6:7]
	v_cndmask_b32_e32 v100, v166, v100, vcc
	v_cmp_gt_i32_e32 vcc, s31, v169
	s_or_b64 s[4:5], s[6:7], s[4:5]
	s_or_b64 vcc, s[4:5], vcc
	v_cndmask_b32_e64 v99, v166, v99, s[8:9]
	v_cndmask_b32_e64 v98, v166, v98, s[6:7]
	v_cndmask_b32_e64 v97, v166, v97, s[4:5]
	v_cndmask_b32_e32 v96, v166, v96, vcc
